# v99 + P2 conv weights staged in LDS by LDS-DMA one chunk ahead (48 global_load_dwordx4 per thread and chunk become ds_read_b128; removes 12 load-wait round trips per chunk)
# speedup vs baseline: 1.0050x; 1.0050x over previous
; #define LAS __attribute__((address_space(3)))
; __device__ __forceinline__ float sigm_f(float x) { return 1.0f / (1.0f + __expf(-x)); }
; __device__ __forceinline__ float softplus_f(float x) { return fmaxf(x, 0.f) + log1pf(__expf(-fabsf(x))); }
; __device__ __forceinline__ void gdn_prep_wg(const bf16* P, const float* SMALL, const float* conv_w, const float* a_log, const float* dt_bias,
;                                             unsigned char* REC, bf16* UF, float* EG, LAS unsigned char* lds, int bh, int n0, int nch) {
;     const int tid = threadIdx.x, lane = tid & 63, wave = __builtin_amdgcn_readfirstlane(tid >> 6);
;     const int b = bh / NH, h = bh % NH;
;     LAS unsigned char* kb = lds + G1_KB;
;     LAS unsigned char* qb = lds + G1_QB;
;     LAS unsigned char* RT = lds + G1_RT;
;     LAS float* Amat = (LAS float*)(lds + G1_AM);
;     LAS float* sc = (LAS float*)(lds + G1_SC);
;     LAS unsigned char* raw = lds + G1_RAW;
;     LAS unsigned char* QKs = lds + G1_QKS;
;     LAS unsigned char* Tb = kb;
;     LAS unsigned char* Ws = qb;
;     const float Aexp = __expf(a_log[h]), dtb = dt_bias[h];
;     float lg_b = 0.f, lg_a = 0.f;
;     unsigned roff[7]; g1_raw_offsets(roff, wave, lane);
;     const char* rbase = (const char*)P + (((size_t)b * SEQ + (size_t)n0 * 64) * LDP + h * HD) * 2 - (size_t)3 * LDP * 2;
;     g1_issue_raw(rbase, roff, raw, wave);
;     if (wave == 0) { const float* sm = SMALL + (size_t)b * SEQ + (size_t)n0 * 64 + lane; lg_b = sm[(size_t)h * M]; lg_a = sm[(size_t)(16 + h) * M]; }
;     for (int k = 0; k < nch; ++k) {
;         const int n = n0 + k, ci = bh * 64 + n;
;         unsigned char* rec = REC + (size_t)ci * GREC;
;         if (wave == 0) {
;             const float be = sigm_f(lg_b);
;             const float g = -Aexp * softplus_f(lg_a + dtb);
.LBB0_320:
	s_lshr_b32 s2, s19, 2
	s_bfe_u32 s28, s2, 0x20004
	s_bfe_u32 s30, s18, 0x20004
	s_and_b32 s3, s2, 15
	s_lshl_b32 s50, s28, 14
	s_lshl_b32 s51, s30, 12
	s_lshl_b32 s48, s3, 8
	s_mul_i32 s29, s28, 0x5800000
	s_lshl_b32 s3, s3, 16
	s_or_b32 s28, s51, s50
	s_and_b32 s2, s2, 63
	s_or_b32 s16, s28, s3
	s_lshl_b32 s2, s2, 6
	s_lshl_b32 s3, s30, 4
	s_mul_i32 s31, s30, 0x1600000
	s_or_b32 s28, s2, s3
	s_add_i32 s29, s29, s31
	s_lshl_b32 s2, s28, 2
	s_bfe_u32 s36, s25, 0x20006
	v_writelane_b32 v255, s19, 51
	s_lshl_b32 s49, s29, 1
	s_lshl_b32 s29, s30, 10
	v_lshl_add_u64 v[96:97], s[16:17], 0, v[88:89]
	s_or_b32 s16, s2, 0x80000
	v_mad_u64_u32 v[98:99], s[2:3], s28, v194, v[90:91]
	s_lshl_b32 s54, s28, 9
	v_mad_u64_u32 v[100:101], s[2:3], s28, v194, v[92:93]
	v_mad_u64_u32 v[102:103], s[2:3], s28, v194, v[94:95]
	s_lshl_b32 s28, s36, 4
	s_lshl_b32 s56, s36, 11
	v_writelane_b32 v255, s18, 52
	s_and_b64 s[2:3], s[8:9], exec
	v_readlane_b32 s2, v255, 9
	s_cselect_b32 s2, 0, s2
	v_or_b32_e32 v19, s27, v152
	v_readlane_b32 s60, v254, 7
	v_or_b32_e32 v17, s28, v156
	v_mov_b32_e32 v18, s2
	s_movk_i32 s2, 0x110
	v_lshlrev_b32_e32 v82, 2, v19
	v_readlane_b32 s66, v254, 13
	v_readlane_b32 s67, v254, 14
	v_mad_u32_u24 v17, v17, s2, v18
	s_mov_b64 s[2:3], 0x6000
	v_lshl_add_u64 v[104:105], s[66:67], 0, v[82:83]
	v_lshl_add_u64 v[106:107], v[104:105], 0, s[2:3]
	s_mov_b64 s[2:3], 0xc000
	v_lshl_add_u64 v[108:109], v[104:105], 0, s[2:3]
	s_mov_b64 s[2:3], 0x12000
	v_lshl_add_u64 v[110:111], v[104:105], 0, s[2:3]
	s_mov_b64 s[2:3], 0x2000
	v_lshl_add_u64 v[112:113], v[104:105], 0, s[2:3]
	s_mov_b64 s[2:3], 0x8000
	v_lshl_add_u64 v[114:115], v[104:105], 0, s[2:3]
	s_mov_b64 s[2:3], 0xe000
	v_lshl_add_u64 v[116:117], v[104:105], 0, s[2:3]
	s_mov_b64 s[2:3], 0x14000
	v_lshl_add_u64 v[118:119], v[104:105], 0, s[2:3]
	s_mov_b64 s[2:3], 0x4000
	s_waitcnt vmcnt(0)
	v_mul_f32_e32 v9, 0x3fb8aa3b, v9
	v_lshl_add_u64 v[120:121], v[104:105], 0, s[2:3]
	s_mov_b64 s[2:3], 0xa000
	v_exp_f32_e32 v208, v9
	v_or_b32_e32 v9, s28, v157
	v_lshl_add_u64 v[122:123], v[104:105], 0, s[2:3]
	s_mov_b64 s[2:3], 0x10000
	v_lshl_add_u64 v[124:125], v[104:105], 0, s[2:3]
	s_mov_b64 s[2:3], 0x16000
	v_cmp_gt_u32_e64 s[18:19], v156, v9
	v_lshl_add_u64 v[126:127], v[104:105], 0, s[2:3]
	v_readlane_b32 s2, v255, 7
	v_writelane_b32 v255, s18, 53
	v_or_b32_e32 v19, 1, v9
	s_lshl_b32 s57, s24, 4
	v_writelane_b32 v255, s19, 54
	v_cmp_le_u32_e64 s[18:19], v156, v9
	s_lshl_b32 s55, s24, 7
	v_or_b32_e32 v20, 2, v9
	v_writelane_b32 v255, s18, 55
	s_cmp_lg_u32 s36, 0
	v_or_b32_e32 v21, 3, v9
	v_writelane_b32 v255, s19, 56
	v_cmp_lt_u32_e64 s[18:19], v156, v9
	s_cselect_b64 s[92:93], -1, 0
	s_cmp_gt_u32 s36, 1
	v_writelane_b32 v255, s18, 57
	v_lshl_add_u32 v209, v9, 2, s2
	v_lshl_add_u32 v211, v19, 2, s2
	v_writelane_b32 v255, s19, 58
	v_cmp_gt_u32_e64 s[18:19], v156, v19
	v_lshl_add_u32 v212, v20, 2, s2
	v_lshl_add_u32 v213, v21, 2, s2
	v_writelane_b32 v255, s18, 59
	s_cselect_b64 s[2:3], -1, 0
	s_cmp_eq_u32 s36, 3
	v_writelane_b32 v255, s19, 60
	v_cmp_gt_u32_e64 s[18:19], v156, v20
	s_cselect_b64 s[94:95], -1, 0
	s_cmp_lt_u32 s25, 64
	v_writelane_b32 v255, s18, 61
	s_cselect_b64 s[36:37], -1, 0
	v_mul_i32_i24_e32 v10, 0xfffffcf0, v10
	v_writelane_b32 v255, s19, 62
	v_readlane_b32 s18, v254, 57
	v_readlane_b32 s19, v254, 58
	s_and_b64 s[36:37], s[18:19], s[36:37]
	s_cmp_eq_u32 s24, 1
	v_cndmask_b32_e64 v214, 0, 1.0, s[36:37]
	s_cselect_b64 s[36:37], -1, 0
	s_and_b64 s[36:37], s[18:19], s[36:37]
	s_cmp_eq_u32 s24, 2
	v_cndmask_b32_e64 v215, 0, 1.0, s[36:37]
	s_cselect_b64 s[36:37], -1, 0
	s_and_b64 s[36:37], s[18:19], s[36:37]
	s_cmp_eq_u32 s24, 3
	v_cndmask_b32_e64 v216, 0, 1.0, s[36:37]
	s_cselect_b64 s[36:37], -1, 0
	s_and_b64 s[36:37], s[18:19], s[36:37]
	s_cmp_eq_u32 s24, 4
	v_cndmask_b32_e64 v217, 0, 1.0, s[36:37]
	s_cselect_b64 s[36:37], -1, 0
	s_and_b64 s[36:37], s[18:19], s[36:37]
	s_cmp_eq_u32 s24, 5
	v_cndmask_b32_e64 v218, 0, 1.0, s[36:37]
	s_cselect_b64 s[36:37], -1, 0
	s_and_b64 s[36:37], s[18:19], s[36:37]
	s_cmp_eq_u32 s24, 6
	v_cndmask_b32_e64 v219, 0, 1.0, s[36:37]
	s_cselect_b64 s[36:37], -1, 0
	s_and_b64 s[36:37], s[18:19], s[36:37]
	s_cmp_eq_u32 s24, 7
	v_lshl_or_b32 v18, s24, 5, v156
	s_cselect_b64 s[24:25], -1, 0
	s_and_b64 s[24:25], s[18:19], s[24:25]
	v_add3_u32 v10, v150, v10, s26
	v_mul_i32_i24_e32 v11, 0xfffffcf0, v11
	v_cndmask_b32_e64 v221, 0, 1.0, s[24:25]
	s_or_b32 s24, s49, s48
	v_and_b32_e32 v10, 0xf0, v10
	s_add_u32 s24, s24, 0x27c9f000
	v_add_u32_e32 v82, v2, v10
	v_add3_u32 v2, v184, v11, s26
	v_mul_i32_i24_e32 v12, 0xfffffcf0, v12
	s_addc_u32 s25, 0, 0
	v_and_b32_e32 v2, 0xf0, v2
	v_lshl_add_u64 v[128:129], s[24:25], 0, v[82:83]
	v_add_u32_e32 v82, v3, v2
	v_add3_u32 v2, v185, v12, s26
	v_mul_i32_i24_e32 v13, 0xfffffcf0, v13
	v_and_b32_e32 v2, 0xf0, v2
; __device__ __forceinline__ float sigm_f(float x) { return 1.0f / (1.0f + __expf(-x)); }
; __device__ __forceinline__ float softplus_f(float x) { return fmaxf(x, 0.f) + log1pf(__expf(-fabsf(x))); }
; #define GBAR() do { asm volatile("s_waitcnt lgkmcnt(0)" ::: "memory"); __builtin_amdgcn_s_barrier(); asm volatile("" ::: "memory"); } while (0)
; __device__ __forceinline__ void gdn_prep_wg(const bf16* P, const float* SMALL, const float* conv_w, const float* a_log, const float* dt_bias,
;                                             unsigned char* REC, bf16* UF, float* EG, LAS unsigned char* lds, int bh, int n0, int nch) {
;     ...
;     const float Aexp = __expf(a_log[h]), dtb = dt_bias[h];
;     float lg_b = 0.f, lg_a = 0.f;
;     unsigned roff[7]; g1_raw_offsets(roff, wave, lane);
;     const char* rbase = (const char*)P + (((size_t)b * SEQ + (size_t)n0 * 64) * LDP + h * HD) * 2 - (size_t)3 * LDP * 2;
;     g1_issue_raw(rbase, roff, raw, wave);
;     if (wave == 0) { const float* sm = SMALL + (size_t)b * SEQ + (size_t)n0 * 64 + lane; lg_b = sm[(size_t)h * M]; lg_a = sm[(size_t)(16 + h) * M]; }
;     for (int k = 0; k < nch; ++k) {
;         const int n = n0 + k, ci = bh * 64 + n;
;         unsigned char* rec = REC + (size_t)ci * GREC;
;         if (wave == 0) {
;             const float be = sigm_f(lg_b);
;             const float g = -Aexp * softplus_f(lg_a + dtb);
;             float gc = g;
; #pragma unroll
;             for (int o = 1; o < 64; o <<= 1) { const float t = __shfl_up(gc, o); if (lane >= o) gc += t; }
;             const float gl = __shfl(gc, 63);
;             sc[lane] = gc; sc[64 + lane] = be; sc[128 + lane] = __expf(gc); sc[192 + lane] = __expf(gl - gc);
;             if (lane == 63) EG[ci] = __expf(gl);
;         }
;         asm volatile("s_waitcnt vmcnt(0)" ::: "memory");
;         GBAR();
;         if (wave == 0 && k + 1 < nch) { const float* sm = SMALL + (size_t)b * SEQ + (size_t)(n + 1) * 64 + lane; lg_b = sm[(size_t)h * M]; lg_a = sm[(size_t)(16 + h) * M]; }
	v_lshl_add_u64 v[130:131], s[24:25], 0, v[82:83]
	v_add_u32_e32 v82, v4, v2
	v_add3_u32 v2, v186, v13, s26
	v_mul_i32_i24_e32 v14, 0xfffffcf0, v14
	v_and_b32_e32 v2, 0xf0, v2
	s_lshl_b64 s[4:5], s[4:5], 2
	v_lshl_add_u64 v[132:133], s[24:25], 0, v[82:83]
	v_add_u32_e32 v82, v5, v2
	v_add3_u32 v2, v187, v14, s26
	s_add_u32 s4, s4, s51
	v_mul_i32_i24_e32 v15, 0xfffffcf0, v15
	v_and_b32_e32 v2, 0xf0, v2
	s_addc_u32 s5, s5, 0
	v_lshl_add_u64 v[134:135], s[24:25], 0, v[82:83]
	v_add_u32_e32 v82, v6, v2
	v_add3_u32 v2, v188, v15, s26
	s_add_u32 s4, s4, s50
	v_mul_i32_i24_e32 v16, 0xfffffcf0, v16
	v_and_b32_e32 v2, 0xf0, v2
	s_addc_u32 s5, s5, 0
	v_lshl_add_u64 v[136:137], s[24:25], 0, v[82:83]
	v_add_u32_e32 v82, v7, v2
	v_add3_u32 v2, v189, v16, s26
	v_lshl_add_u64 v[142:143], s[4:5], 0, v[86:87]
	s_add_u32 s4, s55, s54
	s_movk_i32 s18, 0x90
	v_and_b32_e32 v2, 0xf0, v2
	s_addc_u32 s5, 0, 0
	v_readlane_b32 s61, v254, 8
	v_readlane_b32 s62, v254, 9
	v_readlane_b32 s63, v254, 10
	v_readlane_b32 s64, v254, 11
	v_readlane_b32 s65, v254, 12
	v_readlane_b32 s68, v254, 15
	v_readlane_b32 s69, v254, 16
	v_readlane_b32 s70, v254, 17
	v_readlane_b32 s71, v254, 18
	v_readlane_b32 s72, v254, 19
	v_readlane_b32 s73, v254, 20
	v_readlane_b32 s74, v254, 21
	v_readlane_b32 s75, v254, 22
	v_mul_lo_u32 v18, v18, s18
	v_lshl_add_u64 v[138:139], s[24:25], 0, v[82:83]
	v_add_u32_e32 v82, v8, v2
	v_mov_b32_e32 v3, s5
	v_or_b32_e32 v2, s4, v198
	v_subrev_u32_e32 v207, s29, v190
	v_mul_u32_u24_e32 v210, 0x110, v9
	v_cmp_lt_u32_e64 s[28:29], v156, v20
	v_cmp_gt_u32_e64 s[30:31], v156, v21
	v_cmp_lt_u32_e64 s[34:35], v156, v21
	v_cndmask_b32_e64 v220, 0, 1.0, s[36:37]
	v_cmp_gt_u32_e64 s[36:37], v164, v9
	v_cmp_le_u32_e64 s[38:39], v164, v9
	v_cmp_lt_u32_e64 s[40:41], v164, v9
	v_cmp_gt_u32_e64 s[42:43], v164, v19
	v_cmp_gt_u32_e64 s[44:45], v164, v20
	v_cmp_lt_u32_e64 s[46:47], v164, v20
	v_lshl_add_u64 v[140:141], s[24:25], 0, v[82:83]
	v_cmp_gt_u32_e64 s[48:49], v164, v21
	v_cmp_lt_u32_e64 s[50:51], v164, v21
	v_cmp_gt_u32_e64 s[52:53], v165, v9
	v_cmp_le_u32_e64 s[54:55], v165, v9
	v_add_u32_e32 v82, s57, v175
	v_add_u32_e32 v222, s56, v182
	v_cmp_lt_u32_e64 s[56:57], v165, v9
	v_lshlrev_b64 v[144:145], 5, v[2:3]
	v_add_u32_e32 v223, v17, v158
	v_add_u32_e32 v224, v159, v18
	v_add_u32_e32 v225, s26, v183
	v_cmp_gt_u32_e64 s[58:59], v165, v19
	v_cmp_gt_u32_e64 s[60:61], v165, v20
	v_cmp_lt_u32_e64 s[62:63], v165, v20
	v_cmp_gt_u32_e64 s[64:65], v165, v21
	v_cmp_lt_u32_e64 s[66:67], v165, v21
	v_cmp_gt_u32_e64 s[68:69], v166, v9
	v_cmp_le_u32_e64 s[70:71], v166, v9
	v_cmp_lt_u32_e64 s[72:73], v166, v9
	v_cmp_gt_u32_e64 s[74:75], v166, v19
	v_cmp_gt_u32_e64 s[76:77], v166, v20
	v_cmp_lt_u32_e64 s[78:79], v166, v20
	v_cmp_gt_u32_e64 s[80:81], v166, v21
	v_cmp_lt_u32_e64 s[82:83], v166, v21
	v_lshrrev_b32_e32 v231, 6, v0
	v_bfe_u32 v232, v0, 5, 1
	v_lshl_add_u32 v231, v231, 1, v232
	v_and_b32_e32 v232, 3, v231
	v_lshrrev_b32_e32 v231, 2, v231
	v_mul_u32_u24_e32 v232, 0x6000, v232
	v_lshl_add_u32 v232, v231, 13, v232
	v_and_b32_e32 v231, 31, v0
	v_lshl_add_u32 v232, v231, 4, v232
	v_and_b32_e32 v231, 7, v0
	v_lshlrev_b32_e32 v231, 6, v231
	v_sub_u32_e32 v232, v232, v231
	v_ashrrev_i32_e32 v233, 31, v232
	v_lshl_add_u64 v[228:229], v[104:105], 0, v[232:233]
	v_add_u32_e32 v230, 0x23000, v231
	v_readfirstlane_b32 s32, v0
	s_cmp_lt_u32 s32, 0x180
	s_cbranch_scc0 .Lcw_skipA
	s_lshl_b32 s32, s32, 4
	s_add_i32 m0, s32, 0x23000
	s_nop 0
	global_load_lds_dwordx4 v[228:229], off
.Lcw_skipA:
	s_mov_b64 s[96:97], 0
	s_mov_b32 s27, s17
	s_mov_b64 s[4:5], s[16:17]
	s_branch .LBB0_322
.LBB0_321:
	s_waitcnt lgkmcnt(0)
	s_barrier
	v_readfirstlane_b32 s32, v0
	s_cmp_lt_u32 s32, 0x180
	s_cbranch_scc0 .Lcw_skipB
	s_lshl_b32 s32, s32, 4
	s_add_i32 m0, s32, 0x23000
	s_nop 0
	global_load_lds_dwordx4 v[228:229], off
.Lcw_skipB:
	s_nop 2
	ds_read_b128 v[2:5], v226 offset:17408
	s_add_u32 s96, s96, 0xe000
	s_addc_u32 s97, s97, 0
	s_add_u32 s4, s4, 4
	v_add_co_u32_e32 v6, vcc, 0x2000, v146
	s_waitcnt lgkmcnt(0)
	global_store_dwordx4 v[146:147], v[2:5], off
	ds_read_b128 v[2:5], v226 offset:25600
	s_addc_u32 s5, s5, 0
	s_mov_b64 s[16:17], 0x4000
	v_addc_co_u32_e32 v7, vcc, 0, v147, vcc
	v_lshl_add_u64 v[128:129], v[128:129], 0, s[0:1]
	v_lshl_add_u64 v[130:131], v[130:131], 0, s[0:1]
	v_lshl_add_u64 v[132:133], v[132:133], 0, s[0:1]
	v_lshl_add_u64 v[134:135], v[134:135], 0, s[0:1]
	v_lshl_add_u64 v[136:137], v[136:137], 0, s[0:1]
	v_lshl_add_u64 v[138:139], v[138:139], 0, s[0:1]
	v_lshl_add_u64 v[140:141], v[140:141], 0, s[0:1]
	v_subrev_u32_e32 v207, 64, v207
	v_lshl_add_u64 v[142:143], v[142:143], 0, s[6:7]
	v_lshl_add_u64 v[96:97], v[96:97], 0, s[6:7]
	v_lshl_add_u64 v[144:145], v[144:145], 0, s[16:17]
	s_cmp_lg_u32 s96, 0xe0000
	s_waitcnt lgkmcnt(0)
	global_store_dwordx4 v[6:7], v[2:5], off
	s_cbranch_scc0 .LBB0_301

; #define LAS __attribute__((address_space(3)))
; __device__ __forceinline__ float bflo(unsigned w) { return __uint_as_float(w << 16); }
; __device__ __forceinline__ float bfhi(unsigned w) { return __uint_as_float(w & 0xffff0000u); }
; __device__ __forceinline__ float silu_fast(float x) { return x * __builtin_amdgcn_rcpf(1.0f + __builtin_amdgcn_exp2f(-1.4426950408889634f * x)); }
; __device__ __forceinline__ void gdn_prep_wg(const bf16* P, const float* SMALL, const float* conv_w, const float* a_log, const float* dt_bias,
;                                             unsigned char* REC, bf16* UF, float* EG, LAS unsigned char* lds, int bh, int n0, int nch) {
;     ...
;             for (int ten = 0; ten < 3; ++ten) {
;                 const int pcol = ten * HW + h * HD + c0;
;                 float acc[16];
; #pragma unroll
;                 for (int j = 0; j < 16; ++j) acc[j] = 0.f;
; #pragma unroll
;                 for (int i = 0; i < 4; ++i) {
;                     if (t - 3 + i >= 0) { const LAS unsigned char* src = raw + (row + i) * RAWP + ten * 256 + c0 * 2; const v4u x0 = *(const LAS v4u*)src, x1 = *(const LAS v4u*)(src + 16);
;                         const float* w = conv_w + (size_t)i * CONVW + pcol;
;                         const f32x4 w0 = *(const f32x4*)w, w1 = *(const f32x4*)(w + 4), w2 = *(const f32x4*)(w + 8), w3 = *(const f32x4*)(w + 12);
;                         acc[0] += w0.x * bflo(x0.x); acc[1] += w0.y * bfhi(x0.x); acc[2] += w0.z * bflo(x0.y); acc[3] += w0.w * bfhi(x0.y);
;                         acc[4] += w1.x * bflo(x0.z); acc[5] += w1.y * bfhi(x0.z); acc[6] += w1.z * bflo(x0.w); acc[7] += w1.w * bfhi(x0.w);
;                         acc[8] += w2.x * bflo(x1.x); acc[9] += w2.y * bfhi(x1.x); acc[10] += w2.z * bflo(x1.y); acc[11] += w2.w * bfhi(x1.y);
;                         acc[12] += w3.x * bflo(x1.z); acc[13] += w3.y * bfhi(x1.z); acc[14] += w3.z * bflo(x1.w); acc[15] += w3.w * bfhi(x1.w); } }
;                 float ss = 0.f;
; #pragma unroll
;                 for (int j = 0; j < 16; ++j) { acc[j] = silu_fast(acc[j]); ss += acc[j] * acc[j]; }
.LBB0_331:
	ds_read_b128 v[2:5], v201 offset:1568
	ds_read_b128 v[6:9], v201 offset:1584
	ds_read_b128 v[10:13], v230 offset:1072
	ds_read_b128 v[34:37], v230 offset:1056
	ds_read_b128 v[38:41], v230 offset:1040
	ds_read_b128 v[44:47], v230 offset:1024
	s_waitcnt lgkmcnt(0)
	v_lshlrev_b32_e32 v28, 16, v2
	v_and_b32_e32 v29, 0xffff0000, v2
	v_lshlrev_b32_e32 v2, 16, v3
	v_and_b32_e32 v3, 0xffff0000, v3
	s_waitcnt vmcnt(0) lgkmcnt(0)
	v_pk_fma_f32 v[16:17], v[46:47], v[2:3], v[16:17]
	v_lshlrev_b32_e32 v2, 16, v4
	v_and_b32_e32 v3, 0xffff0000, v4
	v_pk_fma_f32 v[20:21], v[38:39], v[2:3], v[20:21]
	v_lshlrev_b32_e32 v2, 16, v5
	v_and_b32_e32 v3, 0xffff0000, v5
	v_pk_fma_f32 v[22:23], v[40:41], v[2:3], v[22:23]
	v_lshlrev_b32_e32 v2, 16, v6
	v_and_b32_e32 v3, 0xffff0000, v6
	v_pk_fma_f32 v[26:27], v[34:35], v[2:3], v[26:27]
	v_lshlrev_b32_e32 v2, 16, v7
	v_and_b32_e32 v3, 0xffff0000, v7
	v_pk_fma_f32 v[32:33], v[36:37], v[2:3], v[32:33]
	v_lshlrev_b32_e32 v2, 16, v8
	v_and_b32_e32 v3, 0xffff0000, v8
	v_pk_fma_f32 v[30:31], v[10:11], v[2:3], v[30:31]
	v_lshlrev_b32_e32 v2, 16, v9
	v_and_b32_e32 v3, 0xffff0000, v9
	v_pk_fma_f32 v[14:15], v[44:45], v[28:29], v[14:15]
	v_pk_fma_f32 v[24:25], v[12:13], v[2:3], v[24:25]
.LBB0_332:
	s_or_b64 exec, exec, s[90:91]
	ds_read_b128 v[2:5], v230 offset:1536
	ds_read_b128 v[10:13], v230 offset:1552
	ds_read_b128 v[38:41], v230 offset:1568
	ds_read_b128 v[34:37], v230 offset:1584
	ds_read_b128 v[6:9], v201 offset:2352
	ds_read_b128 v[44:47], v201 offset:2368
	v_add_u32_e32 v43, v155, v154
	s_waitcnt lgkmcnt(0)
	v_lshlrev_b32_e32 v28, 16, v47
	v_and_b32_e32 v29, 0xffff0000, v47
	s_waitcnt vmcnt(0) lgkmcnt(0)
	v_pk_fma_f32 v[24:25], v[36:37], v[28:29], v[24:25]
	v_lshlrev_b32_e32 v36, 16, v46
	v_and_b32_e32 v37, 0xffff0000, v46
	v_pk_fma_f32 v[30:31], v[34:35], v[36:37], v[30:31]
	v_lshlrev_b32_e32 v36, 16, v45
	v_and_b32_e32 v37, 0xffff0000, v45
	v_pk_fma_f32 v[32:33], v[40:41], v[36:37], v[32:33]
	v_lshlrev_b32_e32 v40, 16, v44
	v_and_b32_e32 v41, 0xffff0000, v44
	v_pk_fma_f32 v[26:27], v[38:39], v[40:41], v[26:27]
	v_lshlrev_b32_e32 v40, 16, v9
	v_and_b32_e32 v41, 0xffff0000, v9
	v_pk_fma_f32 v[12:13], v[12:13], v[40:41], v[22:23]
	v_lshlrev_b32_e32 v40, 16, v8
	v_mul_f32_e32 v9, 0xbfb8aa3b, v12
	v_exp_f32_e32 v9, v9
	v_and_b32_e32 v41, 0xffff0000, v8
	v_mul_f32_e32 v38, 0xbfb8aa3b, v26
	v_mul_f32_e32 v39, 0xbfb8aa3b, v27
	v_add_f32_e32 v9, 1.0, v9
	v_rcp_f32_e32 v22, v9
	v_mul_f32_e32 v9, 0xbfb8aa3b, v13
	v_exp_f32_e32 v9, v9
	v_exp_f32_e32 v38, v38
	v_exp_f32_e32 v39, v39
	v_mul_f32_e32 v36, 0xbfb8aa3b, v32
	v_add_f32_e32 v9, 1.0, v9
	v_rcp_f32_e32 v23, v9
	v_pk_fma_f32 v[8:9], v[10:11], v[40:41], v[20:21]
	v_lshlrev_b32_e32 v20, 16, v7
	v_and_b32_e32 v21, 0xffff0000, v7
	v_pk_fma_f32 v[4:5], v[4:5], v[20:21], v[16:17]
	v_lshlrev_b32_e32 v20, 16, v6
	v_mul_f32_e32 v7, 0xbfb8aa3b, v4
	v_exp_f32_e32 v7, v7
	v_and_b32_e32 v21, 0xffff0000, v6
	v_pk_fma_f32 v[2:3], v[2:3], v[20:21], v[14:15]
	v_mul_f32_e32 v10, 0xbfb8aa3b, v8
	v_add_f32_e32 v7, 1.0, v7
	v_rcp_f32_e32 v16, v7
	v_mul_f32_e32 v7, 0xbfb8aa3b, v5
	v_exp_f32_e32 v7, v7
	v_mul_f32_e32 v6, 0xbfb8aa3b, v2
	v_exp_f32_e32 v6, v6
	v_mul_f32_e32 v11, 0xbfb8aa3b, v9
	v_add_f32_e32 v7, 1.0, v7
	v_rcp_f32_e32 v17, v7
	v_mul_f32_e32 v7, 0xbfb8aa3b, v3
	v_exp_f32_e32 v7, v7
	v_exp_f32_e32 v10, v10
	v_exp_f32_e32 v11, v11
	v_add_f32_e32 v6, 1.0, v6
	v_add_f32_e32 v7, 1.0, v7
	v_rcp_f32_e32 v6, v6
	v_rcp_f32_e32 v7, v7
	v_add_f32_e32 v10, 1.0, v10
	v_add_f32_e32 v11, 1.0, v11
	v_mul_f32_e32 v37, 0xbfb8aa3b, v33
	v_rcp_f32_e32 v10, v10
	v_rcp_f32_e32 v11, v11
	v_exp_f32_e32 v36, v36
	v_exp_f32_e32 v37, v37
	v_pk_mul_f32 v[6:7], v[2:3], v[6:7]
	v_mul_f32_e32 v34, 0xbfb8aa3b, v30
	v_mul_f32_e32 v35, 0xbfb8aa3b, v31
	v_pk_mul_f32 v[4:5], v[4:5], v[16:17]
	v_pk_mul_f32 v[2:3], v[6:7], v[6:7]
	v_exp_f32_e32 v34, v34
	v_exp_f32_e32 v35, v35
	v_add_f32_e32 v38, 1.0, v38
	v_add_f32_e32 v39, 1.0, v39
	v_pk_mul_f32 v[16:17], v[4:5], v[4:5]
	v_add_f32_e32 v2, v2, v3
	v_mul_f32_e32 v28, 0xbfb8aa3b, v24
	v_mul_f32_e32 v29, 0xbfb8aa3b, v25
	v_rcp_f32_e32 v38, v38
	v_rcp_f32_e32 v39, v39
	v_pk_mul_f32 v[8:9], v[8:9], v[10:11]
	v_add_f32_e32 v2, v16, v2
	v_exp_f32_e32 v28, v28
	v_exp_f32_e32 v29, v29
	v_add_f32_e32 v36, 1.0, v36
	v_add_f32_e32 v37, 1.0, v37
	v_pk_mul_f32 v[10:11], v[8:9], v[8:9]
	v_add_f32_e32 v2, v17, v2
	v_rcp_f32_e32 v36, v36
	v_rcp_f32_e32 v37, v37
	v_pk_mul_f32 v[12:13], v[12:13], v[22:23]
	v_add_f32_e32 v2, v10, v2
	v_add_f32_e32 v34, 1.0, v34
; #define LAS __attribute__((address_space(3)))
; __device__ __forceinline__ unsigned pk2(float lo, float hi) { const f32x2c v = {lo, hi}; return __builtin_bit_cast(unsigned, __builtin_convertvector(v, bf16x2c)); }
; __device__ __forceinline__ float sum8(float v) { v += dppmov<0xB1>(v); v += dppmov<0x4E>(v); v += dppmov<0x141>(v); return v; }
; __device__ __forceinline__ float silu_fast(float x) { return x * __builtin_amdgcn_rcpf(1.0f + __builtin_amdgcn_exp2f(-1.4426950408889634f * x)); }
; __device__ __forceinline__ void gdn_prep_wg(const bf16* P, const float* SMALL, const float* conv_w, const float* a_log, const float* dt_bias,
;                                             unsigned char* REC, bf16* UF, float* EG, LAS unsigned char* lds, int bh, int n0, int nch) {
;     ...
;                 float ss = 0.f;
; #pragma unroll
;                 for (int j = 0; j < 16; ++j) { acc[j] = silu_fast(acc[j]); ss += acc[j] * acc[j]; }
;                 if (ten < 2) { ss = sum8(ss); const float s_ = (1.0f / sqrtf(ss + EPS)) * (ten == 0 ? 0.08838834764831845f : 1.0f);
; #pragma unroll
;                     for (int j = 0; j < 16; ++j) acc[j] *= s_; }
;                 if (ten == 0) {
;                     v4u o0, o1; o0.x = pk2(acc[0], acc[1]); o0.y = pk2(acc[2], acc[3]); o0.z = pk2(acc[4], acc[5]); o0.w = pk2(acc[6], acc[7]);
;                     o1.x = pk2(acc[8], acc[9]); o1.y = pk2(acc[10], acc[11]); o1.z = pk2(acc[12], acc[13]); o1.w = pk2(acc[14], acc[15]);
;                     *(LAS v4u*)(qb + row * 272 + c0 * 2) = o0; *(LAS v4u*)(qb + row * 272 + c0 * 2 + 16) = o1;
;                     unsigned char* dst = rec + GR_Q + ((row >> 4) * 4 + (c0 >> 5)) * 1024 + ((c0 >> 4) & 1) * 8;
; #pragma unroll
;                     for (int i = 0; i < 4; ++i) { v2u w; w.x = pk2(acc[4 * i] * egc, acc[4 * i + 1] * egc); w.y = pk2(acc[4 * i + 2] * egc, acc[4 * i + 3] * egc);
;                         *(v2u*)(dst + ((row & 15) + 16 * i) * 16) = w; }
	v_add_f32_e32 v35, 1.0, v35
	v_pk_mul_f32 v[22:23], v[12:13], v[12:13]
	v_add_f32_e32 v2, v11, v2
	v_rcp_f32_e32 v34, v34
	v_rcp_f32_e32 v35, v35
	v_pk_mul_f32 v[26:27], v[26:27], v[38:39]
	v_add_f32_e32 v2, v22, v2
	v_add_f32_e32 v28, 1.0, v28
	v_add_f32_e32 v29, 1.0, v29
	v_pk_mul_f32 v[38:39], v[26:27], v[26:27]
	v_add_f32_e32 v2, v23, v2
	v_rcp_f32_e32 v28, v28
	v_rcp_f32_e32 v29, v29
	v_pk_mul_f32 v[32:33], v[32:33], v[36:37]
	v_add_f32_e32 v2, v38, v2
	v_pk_mul_f32 v[36:37], v[32:33], v[32:33]
	v_add_f32_e32 v2, v39, v2
	v_pk_mul_f32 v[30:31], v[30:31], v[34:35]
	v_add_f32_e32 v2, v36, v2
	v_pk_mul_f32 v[34:35], v[30:31], v[30:31]
	v_add_f32_e32 v2, v37, v2
	v_pk_mul_f32 v[24:25], v[24:25], v[28:29]
	v_add_f32_e32 v2, v34, v2
	v_pk_mul_f32 v[28:29], v[24:25], v[24:25]
	v_add_f32_e32 v2, v35, v2
	v_add_f32_e32 v2, v28, v2
	v_add_f32_e32 v2, v29, v2
	s_nop 1
	v_add_f32_dpp v2, v2, v2 quad_perm:[1,0,3,2] row_mask:0xf bank_mask:0xf bound_ctrl:1
	s_nop 1
	v_add_f32_dpp v2, v2, v2 quad_perm:[2,3,0,1] row_mask:0xf bank_mask:0xf bound_ctrl:1
	s_nop 1
	v_add_f32_dpp v2, v2, v2 row_half_mirror row_mask:0xf bank_mask:0xf bound_ctrl:1
	v_add_f32_e32 v2, 0x358637bd, v2
	v_cmp_gt_f32_e32 vcc, s33, v2
	v_mul_f32_e32 v3, 0x4f800000, v2
	s_nop 0
	v_cndmask_b32_e32 v3, v2, v3, vcc
	v_sqrt_f32_e32 v10, v3
	v_mov_b32_e32 v2, 0
	v_mov_b32_e32 v34, v2
	v_mov_b32_e32 v35, v2
	v_add_u32_e32 v11, -1, v10
	v_fma_f32 v14, -v11, v10, v3
	v_cmp_ge_f32_e64 s[90:91], 0, v14
	v_add_u32_e32 v14, 1, v10
	s_nop 0
	v_cndmask_b32_e64 v11, v10, v11, s[90:91]
	v_fma_f32 v10, -v14, v10, v3
	v_cmp_lt_f32_e64 s[90:91], 0, v10
	s_nop 1
	v_cndmask_b32_e64 v10, v11, v14, s[90:91]
	v_mul_f32_e32 v11, 0x37800000, v10
	v_cndmask_b32_e32 v10, v10, v11, vcc
	v_cmp_class_f32_e32 vcc, v3, v191
	s_nop 1
	v_cndmask_b32_e32 v3, v10, v3, vcc
	v_div_scale_f32 v10, s[90:91], v3, v3, 1.0
	v_rcp_f32_e32 v11, v10
	s_nop 0
	v_fma_f32 v14, -v10, v11, 1.0
	v_fmac_f32_e32 v11, v14, v11
	v_div_scale_f32 v14, vcc, 1.0, v3, 1.0
	v_mul_f32_e32 v15, v14, v11
	v_fma_f32 v16, -v10, v15, v14
	v_fmac_f32_e32 v15, v16, v11
	v_fma_f32 v10, -v10, v15, v14
	v_div_fmas_f32 v10, v10, v11, v15
	v_div_fixup_f32 v3, v10, v3, 1.0
	v_mul_f32_e32 v10, 0x3db504f3, v3
	v_pk_mul_f32 v[14:15], v[6:7], v[10:11] op_sel_hi:[1,0]
	v_pk_mul_f32 v[16:17], v[4:5], v[10:11] op_sel_hi:[1,0]
	v_pk_mul_f32 v[20:21], v[8:9], v[10:11] op_sel_hi:[1,0]
	v_pk_mul_f32 v[12:13], v[12:13], v[10:11] op_sel_hi:[1,0]
	v_pk_mul_f32 v[22:23], v[26:27], v[10:11] op_sel_hi:[1,0]
	v_pk_mul_f32 v[26:27], v[32:33], v[10:11] op_sel_hi:[1,0]
	v_pk_mul_f32 v[28:29], v[30:31], v[10:11] op_sel_hi:[1,0]
	v_pk_mul_f32 v[24:25], v[24:25], v[10:11] op_sel_hi:[1,0]
	v_cvt_pk_bf16_f32 v4, v14, v15
	v_cvt_pk_bf16_f32 v5, v16, v17
	v_cvt_pk_bf16_f32 v6, v20, v21
	v_cvt_pk_bf16_f32 v7, v12, v13
	v_cvt_pk_bf16_f32 v8, v22, v23
	v_cvt_pk_bf16_f32 v9, v26, v27
	v_cvt_pk_bf16_f32 v10, v28, v29
	v_cvt_pk_bf16_f32 v11, v24, v25
	ds_write_b128 v43, v[4:7] offset:17408
	ds_write_b128 v43, v[8:11] offset:17424
	v_mov_b32_e32 v4, v19
	v_pk_mul_f32 v[6:7], v[4:5], v[14:15] op_sel_hi:[0,1]
	v_pk_mul_f32 v[8:9], v[4:5], v[16:17] op_sel_hi:[0,1]
	v_cvt_pk_bf16_f32 v6, v6, v7
	v_cvt_pk_bf16_f32 v7, v8, v9
	v_lshl_add_u64 v[8:9], v[100:101], 0, s[96:97]
	global_store_dwordx2 v[8:9], v[6:7], off offset:-512
	v_pk_mul_f32 v[6:7], v[4:5], v[20:21] op_sel_hi:[0,1]
	v_pk_mul_f32 v[10:11], v[4:5], v[12:13] op_sel_hi:[0,1]
	v_cvt_pk_bf16_f32 v6, v6, v7
	v_cvt_pk_bf16_f32 v7, v10, v11
	global_store_dwordx2 v[8:9], v[6:7], off offset:-256
	v_pk_mul_f32 v[6:7], v[4:5], v[22:23] op_sel_hi:[0,1]
	v_pk_mul_f32 v[10:11], v[4:5], v[26:27] op_sel_hi:[0,1]
	v_cvt_pk_bf16_f32 v6, v6, v7
	v_cvt_pk_bf16_f32 v7, v10, v11
	global_store_dwordx2 v[8:9], v[6:7], off
	v_pk_mul_f32 v[6:7], v[4:5], v[28:29] op_sel_hi:[0,1]
	v_pk_mul_f32 v[4:5], v[4:5], v[24:25] op_sel_hi:[0,1]
	v_cvt_pk_bf16_f32 v6, v6, v7
	v_cvt_pk_bf16_f32 v7, v4, v5
	v_mov_b32_e32 v3, 0
	v_mov_b32_e32 v14, 0
	v_mov_b32_e32 v15, 0
	v_mov_b32_e32 v16, 0
	v_mov_b32_e32 v17, v2
	v_mov_b32_e32 v22, v2
	v_mov_b32_e32 v23, v2
	v_mov_b32_e32 v24, v2
	v_mov_b32_e32 v25, v2
	v_mov_b32_e32 v28, v2
	v_mov_b32_e32 v29, v2
	v_mov_b32_e32 v30, v2
	v_mov_b32_e32 v31, v2
	v_mov_b32_e32 v26, 0
	v_mov_b32_e32 v27, 0
	global_store_dwordx2 v[8:9], v[6:7], off offset:256
	s_and_saveexec_b64 s[90:91], s[86:87]
	s_cbranch_execnz .LBB0_379
	s_or_b64 exec, exec, s[90:91]
	s_and_saveexec_b64 s[90:91], s[88:89]
	s_cbranch_execnz .LBB0_380

; #define LAS __attribute__((address_space(3)))
; __device__ __forceinline__ float bflo(unsigned w) { return __uint_as_float(w << 16); }
; __device__ __forceinline__ float bfhi(unsigned w) { return __uint_as_float(w & 0xffff0000u); }
; __device__ __forceinline__ float sum8(float v) { v += dppmov<0xB1>(v); v += dppmov<0x4E>(v); v += dppmov<0x141>(v); return v; }
; __device__ __forceinline__ float silu_fast(float x) { return x * __builtin_amdgcn_rcpf(1.0f + __builtin_amdgcn_exp2f(-1.4426950408889634f * x)); }
; __device__ __forceinline__ void gdn_prep_wg(const bf16* P, const float* SMALL, const float* conv_w, const float* a_log, const float* dt_bias,
;                                             unsigned char* REC, bf16* UF, float* EG, LAS unsigned char* lds, int bh, int n0, int nch) {
;     ...
;             for (int ten = 0; ten < 3; ++ten) {
;                 const int pcol = ten * HW + h * HD + c0;
;                 float acc[16];
; #pragma unroll
;                 for (int j = 0; j < 16; ++j) acc[j] = 0.f;
; #pragma unroll
;                 for (int i = 0; i < 4; ++i) {
;                     if (t - 3 + i >= 0) { const LAS unsigned char* src = raw + (row + i) * RAWP + ten * 256 + c0 * 2; const v4u x0 = *(const LAS v4u*)src, x1 = *(const LAS v4u*)(src + 16);
;                         const float* w = conv_w + (size_t)i * CONVW + pcol;
;                         const f32x4 w0 = *(const f32x4*)w, w1 = *(const f32x4*)(w + 4), w2 = *(const f32x4*)(w + 8), w3 = *(const f32x4*)(w + 12);
;                         acc[0] += w0.x * bflo(x0.x); acc[1] += w0.y * bfhi(x0.x); acc[2] += w0.z * bflo(x0.y); acc[3] += w0.w * bfhi(x0.y);
;                         acc[4] += w1.x * bflo(x0.z); acc[5] += w1.y * bfhi(x0.z); acc[6] += w1.z * bflo(x0.w); acc[7] += w1.w * bfhi(x0.w);
;                         acc[8] += w2.x * bflo(x1.x); acc[9] += w2.y * bfhi(x1.x); acc[10] += w2.z * bflo(x1.y); acc[11] += w2.w * bfhi(x1.y);
;                         acc[12] += w3.x * bflo(x1.z); acc[13] += w3.y * bfhi(x1.z); acc[14] += w3.z * bflo(x1.w); acc[15] += w3.w * bfhi(x1.w); } }
;                 float ss = 0.f;
; #pragma unroll
;                 for (int j = 0; j < 16; ++j) { acc[j] = silu_fast(acc[j]); ss += acc[j] * acc[j]; }
;                 if (ten < 2) { ss = sum8(ss); const float s_ = (1.0f / sqrtf(ss + EPS)) * (ten == 0 ? 0.08838834764831845f : 1.0f);
.LBB0_335:
	ds_read_b128 v[2:5], v201 offset:1824
	ds_read_b128 v[6:9], v201 offset:1840
	ds_read_b128 v[10:13], v230 offset:3120
	ds_read_b128 v[36:39], v230 offset:3104
	ds_read_b128 v[44:47], v230 offset:3088
	ds_read_b128 v[48:51], v230 offset:3072
	s_waitcnt lgkmcnt(1)
	v_lshlrev_b32_e32 v20, 16, v2
	v_and_b32_e32 v21, 0xffff0000, v2
	v_lshlrev_b32_e32 v2, 16, v3
	v_and_b32_e32 v3, 0xffff0000, v3
	s_waitcnt vmcnt(0) lgkmcnt(0)
	v_pk_fma_f32 v[16:17], v[50:51], v[2:3], v[16:17]
	v_lshlrev_b32_e32 v2, 16, v4
	v_and_b32_e32 v3, 0xffff0000, v4
	v_pk_fma_f32 v[22:23], v[44:45], v[2:3], v[22:23]
	v_lshlrev_b32_e32 v2, 16, v5
	v_and_b32_e32 v3, 0xffff0000, v5
	v_pk_fma_f32 v[24:25], v[46:47], v[2:3], v[24:25]
	s_waitcnt lgkmcnt(0)
	v_lshlrev_b32_e32 v2, 16, v6
	v_and_b32_e32 v3, 0xffff0000, v6
	v_pk_fma_f32 v[28:29], v[36:37], v[2:3], v[28:29]
	v_lshlrev_b32_e32 v2, 16, v7
	v_and_b32_e32 v3, 0xffff0000, v7
	v_pk_fma_f32 v[34:35], v[38:39], v[2:3], v[34:35]
	v_lshlrev_b32_e32 v2, 16, v8
	v_and_b32_e32 v3, 0xffff0000, v8
	v_pk_fma_f32 v[30:31], v[10:11], v[2:3], v[30:31]
	v_lshlrev_b32_e32 v2, 16, v9
	v_and_b32_e32 v3, 0xffff0000, v9
	v_pk_fma_f32 v[14:15], v[48:49], v[20:21], v[14:15]
	v_pk_fma_f32 v[26:27], v[12:13], v[2:3], v[26:27]
.LBB0_336:
	s_or_b64 exec, exec, s[90:91]
	ds_read_b128 v[2:5], v230 offset:3584
	ds_read_b128 v[10:13], v230 offset:3600
	ds_read_b128 v[44:47], v230 offset:3616
	ds_read_b128 v[36:39], v230 offset:3632
	ds_read_b128 v[6:9], v201 offset:2608
	ds_read_b128 v[48:51], v201 offset:2624
	v_mul_f32_e32 v19, v18, v19
	v_lshl_add_u64 v[20:21], v[102:103], 0, s[96:97]
	s_waitcnt lgkmcnt(0)
	v_lshlrev_b32_e32 v40, 16, v48
	v_and_b32_e32 v41, 0xffff0000, v48
	v_lshlrev_b32_e32 v32, 16, v51
	v_and_b32_e32 v33, 0xffff0000, v51
	s_waitcnt vmcnt(1) lgkmcnt(0)
	v_pk_fma_f32 v[28:29], v[44:45], v[40:41], v[28:29]
	v_lshlrev_b32_e32 v44, 16, v9
	v_and_b32_e32 v45, 0xffff0000, v9
	v_pk_fma_f32 v[12:13], v[12:13], v[44:45], v[24:25]
	v_lshlrev_b32_e32 v44, 16, v8
	v_mul_f32_e32 v9, 0xbfb8aa3b, v12
	v_exp_f32_e32 v9, v9
	v_and_b32_e32 v45, 0xffff0000, v8
	s_waitcnt vmcnt(0) lgkmcnt(0)
	v_pk_fma_f32 v[26:27], v[38:39], v[32:33], v[26:27]
	v_lshlrev_b32_e32 v38, 16, v50
	v_add_f32_e32 v9, 1.0, v9
	v_rcp_f32_e32 v24, v9
	v_mul_f32_e32 v9, 0xbfb8aa3b, v13
	v_exp_f32_e32 v9, v9
	v_and_b32_e32 v39, 0xffff0000, v50
	v_pk_fma_f32 v[30:31], v[36:37], v[38:39], v[30:31]
	v_lshlrev_b32_e32 v38, 16, v49
	v_add_f32_e32 v9, 1.0, v9
	v_rcp_f32_e32 v25, v9
	v_pk_fma_f32 v[8:9], v[10:11], v[44:45], v[22:23]
	v_lshlrev_b32_e32 v22, 16, v7
	v_and_b32_e32 v23, 0xffff0000, v7
	v_pk_fma_f32 v[4:5], v[4:5], v[22:23], v[16:17]
	v_lshlrev_b32_e32 v22, 16, v6
	v_mul_f32_e32 v7, 0xbfb8aa3b, v4
	v_exp_f32_e32 v7, v7
	v_and_b32_e32 v23, 0xffff0000, v6
	v_pk_fma_f32 v[2:3], v[2:3], v[22:23], v[14:15]
	v_mul_f32_e32 v10, 0xbfb8aa3b, v8
	v_add_f32_e32 v7, 1.0, v7
	v_rcp_f32_e32 v16, v7
	v_mul_f32_e32 v7, 0xbfb8aa3b, v5
	v_exp_f32_e32 v7, v7
	v_mul_f32_e32 v6, 0xbfb8aa3b, v2
	v_exp_f32_e32 v6, v6
	v_mul_f32_e32 v11, 0xbfb8aa3b, v9
	v_add_f32_e32 v7, 1.0, v7
	v_rcp_f32_e32 v17, v7
	v_mul_f32_e32 v7, 0xbfb8aa3b, v3
	v_exp_f32_e32 v7, v7
	v_exp_f32_e32 v10, v10
	v_exp_f32_e32 v11, v11
	v_add_f32_e32 v6, 1.0, v6
	v_add_f32_e32 v7, 1.0, v7
	v_rcp_f32_e32 v6, v6
	v_rcp_f32_e32 v7, v7
	v_and_b32_e32 v39, 0xffff0000, v49
	v_mul_f32_e32 v40, 0xbfb8aa3b, v28
	v_mul_f32_e32 v41, 0xbfb8aa3b, v29
	v_pk_fma_f32 v[34:35], v[46:47], v[38:39], v[34:35]
	v_exp_f32_e32 v40, v40
	v_exp_f32_e32 v41, v41
	v_add_f32_e32 v10, 1.0, v10
	v_add_f32_e32 v11, 1.0, v11
	v_mul_f32_e32 v38, 0xbfb8aa3b, v34
	v_mul_f32_e32 v39, 0xbfb8aa3b, v35
	v_rcp_f32_e32 v10, v10
	v_rcp_f32_e32 v11, v11
	v_exp_f32_e32 v38, v38
	v_exp_f32_e32 v39, v39
	v_pk_mul_f32 v[6:7], v[2:3], v[6:7]
	v_mul_f32_e32 v36, 0xbfb8aa3b, v30
	v_mul_f32_e32 v37, 0xbfb8aa3b, v31
	v_pk_mul_f32 v[4:5], v[4:5], v[16:17]
	v_pk_mul_f32 v[2:3], v[6:7], v[6:7]
	v_exp_f32_e32 v36, v36
	v_exp_f32_e32 v37, v37
	v_add_f32_e32 v40, 1.0, v40
	v_add_f32_e32 v41, 1.0, v41
	v_pk_mul_f32 v[16:17], v[4:5], v[4:5]
	v_add_f32_e32 v2, v2, v3
	v_mul_f32_e32 v32, 0xbfb8aa3b, v26
	v_mul_f32_e32 v33, 0xbfb8aa3b, v27
	v_rcp_f32_e32 v40, v40
	v_rcp_f32_e32 v41, v41
	v_pk_mul_f32 v[8:9], v[8:9], v[10:11]
	v_add_f32_e32 v2, v16, v2
	v_exp_f32_e32 v32, v32
	v_exp_f32_e32 v33, v33
	v_add_f32_e32 v38, 1.0, v38
	v_add_f32_e32 v39, 1.0, v39
	v_pk_mul_f32 v[10:11], v[8:9], v[8:9]
	v_add_f32_e32 v2, v17, v2
	v_rcp_f32_e32 v38, v38
	v_rcp_f32_e32 v39, v39
	v_pk_mul_f32 v[12:13], v[12:13], v[24:25]
	v_add_f32_e32 v2, v10, v2
	v_add_f32_e32 v36, 1.0, v36
	v_add_f32_e32 v37, 1.0, v37
	v_pk_mul_f32 v[24:25], v[12:13], v[12:13]
	v_add_f32_e32 v2, v11, v2
	v_rcp_f32_e32 v36, v36
	v_rcp_f32_e32 v37, v37
	v_pk_mul_f32 v[28:29], v[28:29], v[40:41]
	v_add_f32_e32 v2, v24, v2
	v_add_f32_e32 v32, 1.0, v32
	v_add_f32_e32 v33, 1.0, v33
	v_pk_mul_f32 v[40:41], v[28:29], v[28:29]
	v_add_f32_e32 v2, v25, v2
	v_rcp_f32_e32 v32, v32
	v_rcp_f32_e32 v33, v33
	v_pk_mul_f32 v[34:35], v[34:35], v[38:39]
	v_add_f32_e32 v2, v40, v2
	v_pk_mul_f32 v[38:39], v[34:35], v[34:35]
	v_add_f32_e32 v2, v41, v2
	v_pk_mul_f32 v[30:31], v[30:31], v[36:37]
	v_add_f32_e32 v2, v38, v2
	v_pk_mul_f32 v[36:37], v[30:31], v[30:31]
	v_add_f32_e32 v2, v39, v2
	v_pk_mul_f32 v[26:27], v[26:27], v[32:33]
	v_add_f32_e32 v2, v36, v2
	v_pk_mul_f32 v[32:33], v[26:27], v[26:27]
	v_add_f32_e32 v2, v37, v2
	v_add_f32_e32 v2, v32, v2
	v_add_f32_e32 v2, v33, v2
	s_nop 1
	v_add_f32_dpp v2, v2, v2 quad_perm:[1,0,3,2] row_mask:0xf bank_mask:0xf bound_ctrl:1
	s_nop 1
	v_add_f32_dpp v2, v2, v2 quad_perm:[2,3,0,1] row_mask:0xf bank_mask:0xf bound_ctrl:1
; __device__ __forceinline__ void gdn_prep_wg(const bf16* P, const float* SMALL, const float* conv_w, const float* a_log, const float* dt_bias,
;                                             unsigned char* REC, bf16* UF, float* EG, LAS unsigned char* lds, int bh, int n0, int nch) {
;     ...
;                 float ss = 0.f;
; #pragma unroll
;                 for (int j = 0; j < 16; ++j) { acc[j] = silu_fast(acc[j]); ss += acc[j] * acc[j]; }
;                 if (ten < 2) { ss = sum8(ss); const float s_ = (1.0f / sqrtf(ss + EPS)) * (ten == 0 ? 0.08838834764831845f : 1.0f);
; #pragma unroll
;                     for (int j = 0; j < 16; ++j) acc[j] *= s_; }
;                 if (ten == 0) {
;                     v4u o0, o1; o0.x = pk2(acc[0], acc[1]); o0.y = pk2(acc[2], acc[3]); o0.z = pk2(acc[4], acc[5]); o0.w = pk2(acc[6], acc[7]);
;                     o1.x = pk2(acc[8], acc[9]); o1.y = pk2(acc[10], acc[11]); o1.z = pk2(acc[12], acc[13]); o1.w = pk2(acc[14], acc[15]);
;                     *(LAS v4u*)(qb + row * 272 + c0 * 2) = o0; *(LAS v4u*)(qb + row * 272 + c0 * 2 + 16) = o1;
;                     unsigned char* dst = rec + GR_Q + ((row >> 4) * 4 + (c0 >> 5)) * 1024 + ((c0 >> 4) & 1) * 8;
; #pragma unroll
;                     for (int i = 0; i < 4; ++i) { v2u w; w.x = pk2(acc[4 * i] * egc, acc[4 * i + 1] * egc); w.y = pk2(acc[4 * i + 2] * egc, acc[4 * i + 3] * egc);
;                         *(v2u*)(dst + ((row & 15) + 16 * i) * 16) = w; }
;                 } else if (ten == 1) {
;                     v4u o0, o1; o0.x = pk2(acc[0], acc[1]); o0.y = pk2(acc[2], acc[3]); o0.z = pk2(acc[4], acc[5]); o0.w = pk2(acc[6], acc[7]);
;                     o1.x = pk2(acc[8], acc[9]); o1.y = pk2(acc[10], acc[11]); o1.z = pk2(acc[12], acc[13]); o1.w = pk2(acc[14], acc[15]);
;                     *(LAS v4u*)(kb + row * 272 + c0 * 2) = o0; *(LAS v4u*)(kb + row * 272 + c0 * 2 + 16) = o1;
;                     const float bg = be * egc; const int off = row & 31, kq = (off & 15) >> 2, kj = (off & 3) + 4 * (off >> 4);
;                     unsigned char* dst = rec + GR_K + ((c0 >> 4) * 2 + (row >> 5)) * 1024 + (16 * kq) * 16 + kj * 2;
; #pragma unroll
;                     for (int e = 0; e < 16; ++e) { *(LAS bf16*)(RT + (128 + c0 + e) * 144 + row * 2) = (bf16)f2bf(acc[e] * bg);
;                         *(bf16*)(dst + e * 16) = (bf16)f2bf(acc[e] * egl); }
	s_nop 1
	v_add_f32_dpp v2, v2, v2 row_half_mirror row_mask:0xf bank_mask:0xf bound_ctrl:1
	v_add_f32_e32 v2, 0x358637bd, v2
	v_cmp_gt_f32_e32 vcc, s33, v2
	v_mul_f32_e32 v3, 0x4f800000, v2
	s_nop 0
	v_cndmask_b32_e32 v3, v2, v3, vcc
	v_sqrt_f32_e32 v10, v3
	v_mov_b32_e32 v2, 0
	v_mov_b32_e32 v32, v2
	v_mov_b32_e32 v33, v2
	v_add_u32_e32 v11, -1, v10
	v_fma_f32 v14, -v11, v10, v3
	v_cmp_ge_f32_e64 s[90:91], 0, v14
	v_add_u32_e32 v14, 1, v10
	s_nop 0
	v_cndmask_b32_e64 v11, v10, v11, s[90:91]
	v_fma_f32 v10, -v14, v10, v3
	v_cmp_lt_f32_e64 s[90:91], 0, v10
	s_nop 1
	v_cndmask_b32_e64 v10, v11, v14, s[90:91]
	v_mul_f32_e32 v11, 0x37800000, v10
	v_cndmask_b32_e32 v10, v10, v11, vcc
	v_cmp_class_f32_e32 vcc, v3, v191
	s_nop 1
	v_cndmask_b32_e32 v3, v10, v3, vcc
	v_div_scale_f32 v10, s[90:91], v3, v3, 1.0
	v_rcp_f32_e32 v11, v10
	s_nop 0
	v_fma_f32 v14, -v10, v11, 1.0
	v_fmac_f32_e32 v11, v14, v11
	v_div_scale_f32 v14, vcc, 1.0, v3, 1.0
	v_mul_f32_e32 v15, v14, v11
	v_fma_f32 v16, -v10, v15, v14
	v_fmac_f32_e32 v15, v16, v11
	v_fma_f32 v10, -v10, v15, v14
	v_div_fmas_f32 v10, v10, v11, v15
	v_div_fixup_f32 v10, v10, v3, 1.0
	v_pk_mul_f32 v[14:15], v[6:7], v[10:11] op_sel_hi:[1,0]
	v_pk_mul_f32 v[16:17], v[4:5], v[10:11] op_sel_hi:[1,0]
	v_pk_mul_f32 v[22:23], v[8:9], v[10:11] op_sel_hi:[1,0]
	v_pk_mul_f32 v[12:13], v[12:13], v[10:11] op_sel_hi:[1,0]
	v_mul_f32_e32 v3, v19, v14
	v_pk_mul_f32 v[24:25], v[28:29], v[10:11] op_sel_hi:[1,0]
	v_pk_mul_f32 v[28:29], v[34:35], v[10:11] op_sel_hi:[1,0]
	v_pk_mul_f32 v[30:31], v[30:31], v[10:11] op_sel_hi:[1,0]
	v_pk_mul_f32 v[26:27], v[26:27], v[10:11] op_sel_hi:[1,0]
	v_cvt_pk_bf16_f32 v4, v14, v15
	v_cvt_pk_bf16_f32 v5, v16, v17
	v_cvt_pk_bf16_f32 v6, v22, v23
	v_cvt_pk_bf16_f32 v7, v12, v13
	v_cvt_pk_bf16_f32 v3, v3, s0
	v_cvt_pk_bf16_f32 v8, v24, v25
	v_cvt_pk_bf16_f32 v9, v28, v29
	v_cvt_pk_bf16_f32 v10, v30, v31
	v_cvt_pk_bf16_f32 v11, v26, v27
	ds_write_b128 v43, v[4:7]
	ds_write_b128 v43, v[8:11] offset:16
	ds_write_b16 v192, v3 offset:53248
	v_and_b32_e32 v236, 7, v0
	v_lshrrev_b32_e32 v237, 3, v0
	v_lshrrev_b32_e32 v238, 5, v237
	v_lshl_add_u32 v238, v236, 1, v238
	v_lshlrev_b32_e32 v235, 4, v238
	v_lshl_add_u32 v239, v238, 10, v235
	v_bfe_u32 v238, v237, 2, 2
	v_lshl_add_u32 v239, v238, 8, v239
	v_and_b32_e32 v238, 3, v237
	v_lshl_add_u32 v239, v238, 1, v239
	v_bfe_u32 v238, v237, 4, 1
	v_lshl_add_u32 v239, v238, 3, v239
	v_add_u32_e32 v239, 0x11800, v239
	v_mul_f32_e32 v3, v42, v14
	v_cvt_pk_bf16_f32 v3, v3, s0
	ds_write_b16 v239, v3
	v_mul_f32_e32 v3, v19, v15
	v_cvt_pk_bf16_f32 v3, v3, s0
	ds_write_b16 v192, v3 offset:53392
	v_mul_f32_e32 v3, v42, v15
	v_cvt_pk_bf16_f32 v3, v3, s0
	ds_write_b16 v239, v3 offset:16
	v_mul_f32_e32 v3, v19, v16
	v_cvt_pk_bf16_f32 v3, v3, s0
	ds_write_b16 v192, v3 offset:53536
	v_mul_f32_e32 v3, v42, v16
	v_cvt_pk_bf16_f32 v3, v3, s0
	ds_write_b16 v239, v3 offset:32
	v_mul_f32_e32 v3, v19, v17
	v_cvt_pk_bf16_f32 v3, v3, s0
	ds_write_b16 v192, v3 offset:53680
	v_mul_f32_e32 v3, v42, v17
	v_cvt_pk_bf16_f32 v3, v3, s0
	ds_write_b16 v239, v3 offset:48
	v_mul_f32_e32 v3, v19, v22
	v_cvt_pk_bf16_f32 v3, v3, s0
	ds_write_b16 v192, v3 offset:53824
	v_mul_f32_e32 v3, v42, v22
	v_cvt_pk_bf16_f32 v3, v3, s0
	ds_write_b16 v239, v3 offset:64
	v_mul_f32_e32 v3, v19, v23
	v_cvt_pk_bf16_f32 v3, v3, s0
	ds_write_b16 v192, v3 offset:53968
	v_mul_f32_e32 v3, v42, v23
	v_cvt_pk_bf16_f32 v3, v3, s0
	ds_write_b16 v239, v3 offset:80
	v_mul_f32_e32 v3, v19, v12
	v_cvt_pk_bf16_f32 v3, v3, s0
	ds_write_b16 v192, v3 offset:54112
	v_mul_f32_e32 v3, v42, v12
	v_cvt_pk_bf16_f32 v3, v3, s0
	ds_write_b16 v239, v3 offset:96
	v_mul_f32_e32 v3, v19, v13
	v_cvt_pk_bf16_f32 v3, v3, s0
	ds_write_b16 v192, v3 offset:54256
	v_mul_f32_e32 v3, v42, v13
	v_cvt_pk_bf16_f32 v3, v3, s0
	ds_write_b16 v239, v3 offset:112
	v_mul_f32_e32 v3, v19, v24
	v_cvt_pk_bf16_f32 v3, v3, s0
	ds_write_b16 v192, v3 offset:54400
	v_mul_f32_e32 v3, v42, v24
	v_cvt_pk_bf16_f32 v3, v3, s0
	ds_write_b16 v239, v3 offset:128
	v_mul_f32_e32 v3, v19, v25
	v_cvt_pk_bf16_f32 v3, v3, s0
	ds_write_b16 v192, v3 offset:54544
	v_mul_f32_e32 v3, v42, v25
	v_cvt_pk_bf16_f32 v3, v3, s0
	ds_write_b16 v239, v3 offset:144
	v_mul_f32_e32 v3, v19, v28
	v_cvt_pk_bf16_f32 v3, v3, s0
	ds_write_b16 v192, v3 offset:54688
	v_mul_f32_e32 v3, v42, v28
	v_cvt_pk_bf16_f32 v3, v3, s0
	ds_write_b16 v239, v3 offset:160
	v_mul_f32_e32 v3, v19, v29
	v_cvt_pk_bf16_f32 v3, v3, s0
	ds_write_b16 v192, v3 offset:54832
	v_mul_f32_e32 v3, v42, v29
	v_cvt_pk_bf16_f32 v3, v3, s0
	ds_write_b16 v239, v3 offset:176
	v_mul_f32_e32 v3, v19, v30
	v_cvt_pk_bf16_f32 v3, v3, s0
	ds_write_b16 v192, v3 offset:54976
	v_mul_f32_e32 v3, v42, v30
	v_cvt_pk_bf16_f32 v3, v3, s0
	ds_write_b16 v239, v3 offset:192
	v_mul_f32_e32 v3, v19, v31
	v_cvt_pk_bf16_f32 v3, v3, s0
	ds_write_b16 v192, v3 offset:55120
	v_mul_f32_e32 v3, v42, v31
	v_cvt_pk_bf16_f32 v3, v3, s0
	ds_write_b16 v239, v3 offset:208
	v_mul_f32_e32 v3, v19, v26
	v_cvt_pk_bf16_f32 v3, v3, s0
	ds_write_b16 v192, v3 offset:55264
	v_mul_f32_e32 v3, v42, v26
	v_cvt_pk_bf16_f32 v3, v3, s0
	ds_write_b16 v239, v3 offset:224
	v_mul_f32_e32 v3, v19, v27
	v_cvt_pk_bf16_f32 v3, v3, s0
	ds_write_b16 v192, v3 offset:55408
	v_mul_f32_e32 v3, v42, v27
	v_cvt_pk_bf16_f32 v3, v3, s0
	ds_write_b16 v239, v3 offset:240
	v_mov_b32_e32 v3, 0
	v_mov_b32_e32 v20, 0
	v_mov_b32_e32 v21, 0
	v_mov_b32_e32 v22, 0
	v_mov_b32_e32 v23, v2
	v_mov_b32_e32 v24, v2
	v_mov_b32_e32 v25, v2
	v_mov_b32_e32 v26, v2
	v_mov_b32_e32 v27, v2
	v_mov_b32_e32 v28, v2
	v_mov_b32_e32 v29, v2
	v_mov_b32_e32 v30, v2
	v_mov_b32_e32 v31, v2
	v_mov_b32_e32 v34, 0
	v_mov_b32_e32 v35, 0
	s_and_saveexec_b64 s[90:91], s[86:87]
	s_cbranch_execnz .LBB0_381
	s_or_b64 exec, exec, s[90:91]
	s_and_saveexec_b64 s[86:87], s[88:89]
	s_cbranch_execnz .LBB0_382

; #define LAS __attribute__((address_space(3)))
; __device__ __forceinline__ float bflo(unsigned w) { return __uint_as_float(w << 16); }
; __device__ __forceinline__ float bfhi(unsigned w) { return __uint_as_float(w & 0xffff0000u); }
; __device__ __forceinline__ void gdn_prep_wg(const bf16* P, const float* SMALL, const float* conv_w, const float* a_log, const float* dt_bias,
;                                             unsigned char* REC, bf16* UF, float* EG, LAS unsigned char* lds, int bh, int n0, int nch) {
;     ...
;                 for (int i = 0; i < 4; ++i) {
;                     if (t - 3 + i >= 0) { const LAS unsigned char* src = raw + (row + i) * RAWP + ten * 256 + c0 * 2; const v4u x0 = *(const LAS v4u*)src, x1 = *(const LAS v4u*)(src + 16);
;                         const float* w = conv_w + (size_t)i * CONVW + pcol;
;                         const f32x4 w0 = *(const f32x4*)w, w1 = *(const f32x4*)(w + 4), w2 = *(const f32x4*)(w + 8), w3 = *(const f32x4*)(w + 12);
;                         acc[0] += w0.x * bflo(x0.x); acc[1] += w0.y * bfhi(x0.x); acc[2] += w0.z * bflo(x0.y); acc[3] += w0.w * bfhi(x0.y);
;                         acc[4] += w1.x * bflo(x0.z); acc[5] += w1.y * bfhi(x0.z); acc[6] += w1.z * bflo(x0.w); acc[7] += w1.w * bfhi(x0.w);
;                         acc[8] += w2.x * bflo(x1.x); acc[9] += w2.y * bfhi(x1.x); acc[10] += w2.z * bflo(x1.y); acc[11] += w2.w * bfhi(x1.y);
;                         acc[12] += w3.x * bflo(x1.z); acc[13] += w3.y * bfhi(x1.z); acc[14] += w3.z * bflo(x1.w); acc[15] += w3.w * bfhi(x1.w); } }
.LBB0_339:
	ds_read_b128 v[2:5], v201 offset:2080
	ds_read_b128 v[6:9], v201 offset:2096
	ds_read_b128 v[10:13], v230 offset:5168
	ds_read_b128 v[14:17], v230 offset:5152
	ds_read_b128 v[36:39], v230 offset:5136
	ds_read_b128 v[40:43], v230 offset:5120
	s_waitcnt lgkmcnt(1)
	v_lshlrev_b32_e32 v44, 16, v2
	v_and_b32_e32 v45, 0xffff0000, v2
	v_lshlrev_b32_e32 v2, 16, v3
	v_and_b32_e32 v3, 0xffff0000, v3
	s_waitcnt vmcnt(0) lgkmcnt(0)
	v_pk_fma_f32 v[22:23], v[42:43], v[2:3], v[22:23]
	v_lshlrev_b32_e32 v2, 16, v4
	v_and_b32_e32 v3, 0xffff0000, v4
	v_pk_fma_f32 v[24:25], v[36:37], v[2:3], v[24:25]
	v_lshlrev_b32_e32 v2, 16, v5
	v_and_b32_e32 v3, 0xffff0000, v5
	v_pk_fma_f32 v[26:27], v[38:39], v[2:3], v[26:27]
	s_waitcnt lgkmcnt(0)
	v_lshlrev_b32_e32 v2, 16, v6
	v_and_b32_e32 v3, 0xffff0000, v6
	v_pk_fma_f32 v[28:29], v[14:15], v[2:3], v[28:29]
	v_lshlrev_b32_e32 v2, 16, v7
	v_and_b32_e32 v3, 0xffff0000, v7
	v_pk_fma_f32 v[30:31], v[16:17], v[2:3], v[30:31]
	v_lshlrev_b32_e32 v2, 16, v8
	v_and_b32_e32 v3, 0xffff0000, v8
	v_pk_fma_f32 v[32:33], v[10:11], v[2:3], v[32:33]
	v_lshlrev_b32_e32 v2, 16, v9
	v_and_b32_e32 v3, 0xffff0000, v9
	v_pk_fma_f32 v[20:21], v[40:41], v[44:45], v[20:21]
	v_pk_fma_f32 v[34:35], v[12:13], v[2:3], v[34:35]
; #define LAS __attribute__((address_space(3)))
; __device__ __forceinline__ unsigned f2bf(float f) { return pk2(f, f) & 0xffffu; }
; __device__ __forceinline__ float bflo(unsigned w) { return __uint_as_float(w << 16); }
; __device__ __forceinline__ float bfhi(unsigned w) { return __uint_as_float(w & 0xffff0000u); }
; __device__ __forceinline__ float silu_fast(float x) { return x * __builtin_amdgcn_rcpf(1.0f + __builtin_amdgcn_exp2f(-1.4426950408889634f * x)); }
; #define GBAR() do { asm volatile("s_waitcnt lgkmcnt(0)" ::: "memory"); __builtin_amdgcn_s_barrier(); asm volatile("" ::: "memory"); } while (0)
; __device__ __forceinline__ void gdn_prep_wg(const bf16* P, const float* SMALL, const float* conv_w, const float* a_log, const float* dt_bias,
;                                             unsigned char* REC, bf16* UF, float* EG, LAS unsigned char* lds, int bh, int n0, int nch) {
;     ...
;                     if (t - 3 + i >= 0) { const LAS unsigned char* src = raw + (row + i) * RAWP + ten * 256 + c0 * 2; const v4u x0 = *(const LAS v4u*)src, x1 = *(const LAS v4u*)(src + 16);
;                         const float* w = conv_w + (size_t)i * CONVW + pcol;
;                         const f32x4 w0 = *(const f32x4*)w, w1 = *(const f32x4*)(w + 4), w2 = *(const f32x4*)(w + 8), w3 = *(const f32x4*)(w + 12);
;                         acc[0] += w0.x * bflo(x0.x); acc[1] += w0.y * bfhi(x0.x); acc[2] += w0.z * bflo(x0.y); acc[3] += w0.w * bfhi(x0.y);
;                         acc[4] += w1.x * bflo(x0.z); acc[5] += w1.y * bfhi(x0.z); acc[6] += w1.z * bflo(x0.w); acc[7] += w1.w * bfhi(x0.w);
;                         acc[8] += w2.x * bflo(x1.x); acc[9] += w2.y * bfhi(x1.x); acc[10] += w2.z * bflo(x1.y); acc[11] += w2.w * bfhi(x1.y);
;                         acc[12] += w3.x * bflo(x1.z); acc[13] += w3.y * bfhi(x1.z); acc[14] += w3.z * bflo(x1.w); acc[15] += w3.w * bfhi(x1.w); } }
;                 float ss = 0.f;
; #pragma unroll
;                 for (int j = 0; j < 16; ++j) { acc[j] = silu_fast(acc[j]); ss += acc[j] * acc[j]; }
;     ...
;                 } else {
; #pragma unroll
;                     for (int e = 0; e < 16; ++e) *(LAS bf16*)(RT + (c0 + e) * 144 + row * 2) = (bf16)f2bf(acc[e] * be);
;                 }
;             }
;         }
;         GBAR();
;         if (k + 1 < nch) g1_issue_raw(rbase + (size_t)(k + 1) * 64 * LDP * 2, roff, raw, wave);
.LBB0_340:
	s_or_b64 exec, exec, s[86:87]
	ds_read_b128 v[2:5], v230 offset:5632
	ds_read_b128 v[10:13], v230 offset:5648
	ds_read_b128 v[14:17], v230 offset:5664
	ds_read_b128 v[36:39], v230 offset:5680
	ds_read_b128 v[6:9], v201 offset:2864
	ds_read_b128 v[40:43], v201 offset:2880
	s_andn2_b64 vcc, exec, s[24:25]
	s_waitcnt lgkmcnt(0)
	v_and_b32_e32 v19, 0xffff0000, v43
	s_waitcnt vmcnt(0) lgkmcnt(0)
	v_fmac_f32_e32 v35, v39, v19
	v_mul_f32_e32 v19, 0xbfb8aa3b, v35
	v_exp_f32_e32 v19, v19
	s_nop 0
	v_add_f32_e32 v19, 1.0, v19
	v_rcp_f32_e32 v19, v19
	s_nop 0
	v_mul_f32_e32 v19, v35, v19
	v_lshlrev_b32_e32 v35, 16, v43
	v_fmac_f32_e32 v34, v38, v35
	v_mul_f32_e32 v35, 0xbfb8aa3b, v34
	v_exp_f32_e32 v35, v35
	s_nop 0
	v_add_f32_e32 v35, 1.0, v35
	v_rcp_f32_e32 v35, v35
	s_nop 0
	v_mul_f32_e32 v34, v34, v35
	v_and_b32_e32 v35, 0xffff0000, v42
	v_fmac_f32_e32 v33, v37, v35
	v_mul_f32_e32 v35, 0xbfb8aa3b, v33
	v_exp_f32_e32 v35, v35
	s_nop 0
	v_add_f32_e32 v35, 1.0, v35
	v_rcp_f32_e32 v35, v35
	s_nop 0
	v_mul_f32_e32 v33, v33, v35
	v_lshlrev_b32_e32 v35, 16, v42
	v_fmac_f32_e32 v32, v36, v35
	v_mul_f32_e32 v35, 0xbfb8aa3b, v32
	v_exp_f32_e32 v35, v35
	s_nop 0
	v_add_f32_e32 v35, 1.0, v35
	v_rcp_f32_e32 v35, v35
	s_nop 0
	v_mul_f32_e32 v32, v32, v35
	v_and_b32_e32 v35, 0xffff0000, v41
	v_fmac_f32_e32 v31, v17, v35
	v_mul_f32_e32 v17, 0xbfb8aa3b, v31
	v_exp_f32_e32 v17, v17
	s_nop 0
	v_add_f32_e32 v17, 1.0, v17
	v_rcp_f32_e32 v17, v17
	s_nop 0
	v_mul_f32_e32 v17, v31, v17
	v_lshlrev_b32_e32 v31, 16, v41
	v_fmac_f32_e32 v30, v16, v31
	v_mul_f32_e32 v16, 0xbfb8aa3b, v30
	v_exp_f32_e32 v16, v16
	s_nop 0
	v_add_f32_e32 v16, 1.0, v16
	v_rcp_f32_e32 v16, v16
	s_nop 0
	v_mul_f32_e32 v16, v30, v16
	v_and_b32_e32 v30, 0xffff0000, v40
	v_fmac_f32_e32 v29, v15, v30
	v_mul_f32_e32 v15, 0xbfb8aa3b, v29
	v_exp_f32_e32 v15, v15
	s_nop 0
	v_add_f32_e32 v15, 1.0, v15
	v_rcp_f32_e32 v15, v15
	s_nop 0
	v_mul_f32_e32 v15, v29, v15
	v_lshlrev_b32_e32 v29, 16, v40
	v_fmac_f32_e32 v28, v14, v29
	v_mul_f32_e32 v14, 0xbfb8aa3b, v28
	v_exp_f32_e32 v14, v14
	s_nop 0
	v_add_f32_e32 v14, 1.0, v14
	v_rcp_f32_e32 v14, v14
	s_nop 0
	v_mul_f32_e32 v14, v28, v14
	v_and_b32_e32 v28, 0xffff0000, v9
	v_lshlrev_b32_e32 v9, 16, v9
	v_fmac_f32_e32 v26, v12, v9
	v_and_b32_e32 v12, 0xffff0000, v8
	v_lshlrev_b32_e32 v8, 16, v8
	v_fmac_f32_e32 v24, v10, v8
	v_and_b32_e32 v10, 0xffff0000, v7
	v_lshlrev_b32_e32 v7, 16, v7
	v_fmac_f32_e32 v22, v4, v7
	v_and_b32_e32 v7, 0xffff0000, v6
	v_lshlrev_b32_e32 v6, 16, v6
	v_fmac_f32_e32 v20, v2, v6
	v_mul_f32_e32 v2, 0xbfb8aa3b, v20
	v_fmac_f32_e32 v21, v3, v7
	v_exp_f32_e32 v2, v2
	v_mul_f32_e32 v3, 0xbfb8aa3b, v21
	v_exp_f32_e32 v3, v3
	v_mul_f32_e32 v4, 0xbfb8aa3b, v22
	v_fmac_f32_e32 v23, v5, v10
	v_exp_f32_e32 v4, v4
	v_add_f32_e32 v2, 1.0, v2
	v_mul_f32_e32 v5, 0xbfb8aa3b, v23
	v_rcp_f32_e32 v2, v2
	v_exp_f32_e32 v5, v5
	v_add_f32_e32 v3, 1.0, v3
	v_mul_f32_e32 v8, 0xbfb8aa3b, v24
	v_rcp_f32_e32 v3, v3
	v_fmac_f32_e32 v25, v11, v12
	v_exp_f32_e32 v8, v8
	v_add_f32_e32 v4, 1.0, v4
	v_mul_f32_e32 v11, 0xbfb8aa3b, v25
	v_rcp_f32_e32 v4, v4
	v_mul_f32_e32 v2, v20, v2
	v_exp_f32_e32 v11, v11
	v_add_f32_e32 v5, 1.0, v5
	v_mul_f32_e32 v2, v18, v2
	v_mul_f32_e32 v9, 0xbfb8aa3b, v26
	v_rcp_f32_e32 v5, v5
	v_mul_f32_e32 v3, v21, v3
	v_cvt_pk_bf16_f32 v2, v2, s0
	v_fmac_f32_e32 v27, v13, v28
	v_exp_f32_e32 v9, v9
	v_add_f32_e32 v8, 1.0, v8
	ds_write_b16 v193, v2 offset:34816
	v_mul_f32_e32 v2, v18, v3
	v_mul_f32_e32 v13, 0xbfb8aa3b, v27
	v_rcp_f32_e32 v8, v8
	v_mul_f32_e32 v4, v22, v4
	v_cvt_pk_bf16_f32 v2, v2, s0
	v_exp_f32_e32 v13, v13
	v_add_f32_e32 v11, 1.0, v11
	ds_write_b16 v193, v2 offset:34960
	v_mul_f32_e32 v2, v18, v4
	v_rcp_f32_e32 v11, v11
	v_mul_f32_e32 v5, v23, v5
	v_cvt_pk_bf16_f32 v2, v2, s0
	v_add_f32_e32 v9, 1.0, v9
	ds_write_b16 v193, v2 offset:35104
	v_mul_f32_e32 v2, v18, v5
	v_rcp_f32_e32 v9, v9
	v_mul_f32_e32 v8, v24, v8
	v_cvt_pk_bf16_f32 v2, v2, s0
	v_add_f32_e32 v13, 1.0, v13
	ds_write_b16 v193, v2 offset:35248
	v_mul_f32_e32 v2, v18, v8
	v_rcp_f32_e32 v13, v13
	v_mul_f32_e32 v11, v25, v11
	v_cvt_pk_bf16_f32 v2, v2, s0
	ds_write_b16 v193, v2 offset:35392
	v_mul_f32_e32 v2, v18, v11
	v_mul_f32_e32 v9, v26, v9
	v_cvt_pk_bf16_f32 v2, v2, s0
	ds_write_b16 v193, v2 offset:35536
	v_mul_f32_e32 v2, v18, v9
	v_mul_f32_e32 v13, v27, v13
	v_cvt_pk_bf16_f32 v2, v2, s0
	ds_write_b16 v193, v2 offset:35680
	v_mul_f32_e32 v2, v18, v13
	v_cvt_pk_bf16_f32 v2, v2, s0
	ds_write_b16 v193, v2 offset:35824
	v_mul_f32_e32 v2, v18, v14
	v_cvt_pk_bf16_f32 v2, v2, s0
	ds_write_b16 v193, v2 offset:35968
	v_mul_f32_e32 v2, v18, v15
	v_cvt_pk_bf16_f32 v2, v2, s0
	ds_write_b16 v193, v2 offset:36112
	v_mul_f32_e32 v2, v18, v16
	v_cvt_pk_bf16_f32 v2, v2, s0
	ds_write_b16 v193, v2 offset:36256
	v_mul_f32_e32 v2, v18, v17
	v_cvt_pk_bf16_f32 v2, v2, s0
	ds_write_b16 v193, v2 offset:36400
	v_mul_f32_e32 v2, v18, v32
	v_cvt_pk_bf16_f32 v2, v2, s0
	ds_write_b16 v193, v2 offset:36544
	v_mul_f32_e32 v2, v18, v33
	v_cvt_pk_bf16_f32 v2, v2, s0
	ds_write_b16 v193, v2 offset:36688
	v_mul_f32_e32 v2, v18, v34
	v_cvt_pk_bf16_f32 v2, v2, s0
	ds_write_b16 v193, v2 offset:36832
	v_mul_f32_e32 v2, v18, v19
	v_cvt_pk_bf16_f32 v2, v2, s0
	ds_write_b16 v193, v2 offset:36976
	s_waitcnt lgkmcnt(0)
	s_barrier
	v_lshlrev_b32_e32 v240, 4, v0
	v_lshrrev_b32_e32 v242, 6, v0
	v_lshl_add_u32 v241, v242, 4, v240
	v_add_u32_e32 v241, 0x11800, v241
	ds_read_b128 v[244:247], v241
	ds_read_b128 v[248:251], v241 offset:8320
	v_add_u32_e32 v242, 0x11780, v240
	v_sub_u32_e32 v242, v242, v239
	v_add_u32_e32 v242, v242, v235
	v_ashrrev_i32_e32 v243, 31, v242
	v_lshl_add_u64 v[236:237], v[102:103], 0, v[242:243]
	v_lshl_add_u64 v[236:237], v[236:237], 0, s[96:97]
	v_add_u32_e32 v242, 0x2000, v242
	v_ashrrev_i32_e32 v243, 31, v242
	v_lshl_add_u64 v[252:253], v[102:103], 0, v[242:243]
	v_lshl_add_u64 v[252:253], v[252:253], 0, s[96:97]
	s_waitcnt lgkmcnt(0)
	s_barrier
	global_store_dwordx4 v[236:237], v[244:247], off
	global_store_dwordx4 v[252:253], v[248:251], off
	s_cbranch_vccnz .LBB0_355
	v_readlane_b32 s16, v255, 39
	v_readlane_b32 s17, v255, 40
	s_andn2_b64 vcc, exec, s[16:17]
	s_cbranch_vccnz .LBB0_343
	v_readlane_b32 s16, v254, 41
	v_readlane_b32 s20, v254, 45
	v_readlane_b32 s21, v254, 46
	s_add_i32 s24, s26, 0
	s_add_i32 m0, s24, 0x16000
	v_lshl_add_u64 v[2:3], s[20:21], 0, v[128:129]
	global_load_lds_dwordx4 v[2:3], off
	v_readlane_b32 s17, v254, 42
	v_readlane_b32 s18, v254, 43
	v_readlane_b32 s19, v254, 44
	v_readlane_b32 s22, v254, 47
	v_readlane_b32 s23, v254, 48

; #define LAS __attribute__((address_space(3)))
; __device__ __forceinline__ float bflo(unsigned w) { return __uint_as_float(w << 16); }
; __device__ __forceinline__ float bfhi(unsigned w) { return __uint_as_float(w & 0xffff0000u); }
; __device__ __forceinline__ void gdn_prep_wg(const bf16* P, const float* SMALL, const float* conv_w, const float* a_log, const float* dt_bias,
;                                             unsigned char* REC, bf16* UF, float* EG, LAS unsigned char* lds, int bh, int n0, int nch) {
;     ...
;                 for (int i = 0; i < 4; ++i) {
;                     if (t - 3 + i >= 0) { const LAS unsigned char* src = raw + (row + i) * RAWP + ten * 256 + c0 * 2; const v4u x0 = *(const LAS v4u*)src, x1 = *(const LAS v4u*)(src + 16);
;                         const float* w = conv_w + (size_t)i * CONVW + pcol;
;                         const f32x4 w0 = *(const f32x4*)w, w1 = *(const f32x4*)(w + 4), w2 = *(const f32x4*)(w + 8), w3 = *(const f32x4*)(w + 12);
;                         acc[0] += w0.x * bflo(x0.x); acc[1] += w0.y * bfhi(x0.x); acc[2] += w0.z * bflo(x0.y); acc[3] += w0.w * bfhi(x0.y);
;                         acc[4] += w1.x * bflo(x0.z); acc[5] += w1.y * bfhi(x0.z); acc[6] += w1.z * bflo(x0.w); acc[7] += w1.w * bfhi(x0.w);
;                         acc[8] += w2.x * bflo(x1.x); acc[9] += w2.y * bfhi(x1.x); acc[10] += w2.z * bflo(x1.y); acc[11] += w2.w * bfhi(x1.y);
;                         acc[12] += w3.x * bflo(x1.z); acc[13] += w3.y * bfhi(x1.z); acc[14] += w3.z * bflo(x1.w); acc[15] += w3.w * bfhi(x1.w); } }
.LBB0_377:
	ds_read_b128 v[2:5], v201
	ds_read_b128 v[6:9], v201 offset:16
	ds_read_b128 v[10:13], v230 offset:48
	ds_read_b128 v[26:29], v230 offset:32
	ds_read_b128 v[20:23], v230 offset:16
	ds_read_b128 v[14:17], v230 offset:0
	s_waitcnt lgkmcnt(0)
	v_lshlrev_b32_e32 v24, 16, v2
	v_and_b32_e32 v25, 0xffff0000, v2
	v_lshlrev_b32_e32 v2, 16, v3
	v_and_b32_e32 v3, 0xffff0000, v3
	s_waitcnt vmcnt(0) lgkmcnt(0)
	v_pk_fma_f32 v[16:17], v[16:17], v[2:3], 0 op_sel_hi:[1,1,0]
	v_lshlrev_b32_e32 v2, 16, v4
	v_and_b32_e32 v3, 0xffff0000, v4
	v_pk_fma_f32 v[20:21], v[20:21], v[2:3], 0 op_sel_hi:[1,1,0]
	v_lshlrev_b32_e32 v2, 16, v5
	v_and_b32_e32 v3, 0xffff0000, v5
	v_pk_fma_f32 v[22:23], v[22:23], v[2:3], 0 op_sel_hi:[1,1,0]
	v_lshlrev_b32_e32 v2, 16, v6
	v_and_b32_e32 v3, 0xffff0000, v6
	v_pk_fma_f32 v[26:27], v[26:27], v[2:3], 0 op_sel_hi:[1,1,0]
	v_lshlrev_b32_e32 v2, 16, v7
	v_and_b32_e32 v3, 0xffff0000, v7
	v_pk_fma_f32 v[32:33], v[28:29], v[2:3], 0 op_sel_hi:[1,1,0]
	v_lshlrev_b32_e32 v2, 16, v8
	v_and_b32_e32 v3, 0xffff0000, v8
	v_pk_fma_f32 v[30:31], v[10:11], v[2:3], 0 op_sel_hi:[1,1,0]
	v_lshlrev_b32_e32 v2, 16, v9
	v_and_b32_e32 v3, 0xffff0000, v9
	v_pk_fma_f32 v[2:3], v[12:13], v[2:3], 0 op_sel_hi:[1,1,0]
	v_pk_fma_f32 v[14:15], v[14:15], v[24:25], 0 op_sel_hi:[1,1,0]
	v_mov_b32_e32 v24, v2
	v_mov_b32_e32 v25, v3
	s_or_b64 exec, exec, s[84:85]
	v_cmp_gt_i32_e64 s[88:89], 1, v207
	s_and_saveexec_b64 s[84:85], s[88:89]
	s_cbranch_execz .LBB0_330
.LBB0_378:
	ds_read_b128 v[4:7], v201 offset:784
	ds_read_b128 v[8:11], v201 offset:800
	ds_read_b128 v[34:37], v230 offset:560
	ds_read_b128 v[38:41], v230 offset:544
	ds_read_b128 v[44:47], v230 offset:528
	ds_read_b128 v[48:51], v230 offset:512
	s_waitcnt lgkmcnt(0)
	v_lshlrev_b32_e32 v12, 16, v4
	v_and_b32_e32 v13, 0xffff0000, v4
	v_lshlrev_b32_e32 v4, 16, v5
	v_and_b32_e32 v5, 0xffff0000, v5
	s_waitcnt vmcnt(0) lgkmcnt(0)
	v_pk_fma_f32 v[16:17], v[50:51], v[4:5], v[16:17]
	v_lshlrev_b32_e32 v4, 16, v6
	v_and_b32_e32 v5, 0xffff0000, v6
	v_pk_fma_f32 v[20:21], v[44:45], v[4:5], v[20:21]
	v_lshlrev_b32_e32 v4, 16, v7
	v_and_b32_e32 v5, 0xffff0000, v7
	v_pk_fma_f32 v[22:23], v[46:47], v[4:5], v[22:23]
	v_lshlrev_b32_e32 v4, 16, v8
	v_and_b32_e32 v5, 0xffff0000, v8
	v_pk_fma_f32 v[26:27], v[38:39], v[4:5], v[26:27]
	v_lshlrev_b32_e32 v4, 16, v9
	v_and_b32_e32 v5, 0xffff0000, v9
	v_pk_fma_f32 v[32:33], v[40:41], v[4:5], v[32:33]
	v_lshlrev_b32_e32 v4, 16, v10
	v_and_b32_e32 v5, 0xffff0000, v10
	v_pk_fma_f32 v[30:31], v[34:35], v[4:5], v[30:31]
	v_lshlrev_b32_e32 v4, 16, v11
	v_and_b32_e32 v5, 0xffff0000, v11
	v_pk_fma_f32 v[14:15], v[48:49], v[12:13], v[14:15]
	v_pk_fma_f32 v[24:25], v[36:37], v[4:5], v[2:3]
	s_or_b64 exec, exec, s[84:85]
	v_cmp_gt_i32_e64 s[84:85], 2, v207
	s_and_saveexec_b64 s[90:91], s[84:85]
	s_cbranch_execnz .LBB0_331
	s_branch .LBB0_332
.LBB0_379:
	ds_read_b128 v[2:5], v201 offset:256
	ds_read_b128 v[6:9], v201 offset:272
	ds_read_b128 v[10:13], v230 offset:2096
	ds_read_b128 v[28:31], v230 offset:2080
	ds_read_b128 v[22:25], v230 offset:2064
	ds_read_b128 v[14:17], v230 offset:2048
	s_waitcnt lgkmcnt(1)
	v_lshlrev_b32_e32 v20, 16, v2
	v_and_b32_e32 v21, 0xffff0000, v2
	v_lshlrev_b32_e32 v2, 16, v3
	v_and_b32_e32 v3, 0xffff0000, v3
	s_waitcnt vmcnt(0) lgkmcnt(0)
	v_pk_fma_f32 v[16:17], v[16:17], v[2:3], 0 op_sel_hi:[1,1,0]
	v_lshlrev_b32_e32 v2, 16, v4
	v_and_b32_e32 v3, 0xffff0000, v4
	v_pk_fma_f32 v[22:23], v[22:23], v[2:3], 0 op_sel_hi:[1,1,0]
	v_lshlrev_b32_e32 v2, 16, v5
	v_and_b32_e32 v3, 0xffff0000, v5
	v_pk_fma_f32 v[24:25], v[24:25], v[2:3], 0 op_sel_hi:[1,1,0]
	s_waitcnt lgkmcnt(0)
	v_lshlrev_b32_e32 v2, 16, v6
	v_and_b32_e32 v3, 0xffff0000, v6
	v_pk_fma_f32 v[28:29], v[28:29], v[2:3], 0 op_sel_hi:[1,1,0]
	v_lshlrev_b32_e32 v2, 16, v7
	v_and_b32_e32 v3, 0xffff0000, v7
	v_pk_fma_f32 v[34:35], v[30:31], v[2:3], 0 op_sel_hi:[1,1,0]
	v_lshlrev_b32_e32 v2, 16, v8
	v_and_b32_e32 v3, 0xffff0000, v8
	v_pk_fma_f32 v[30:31], v[10:11], v[2:3], 0 op_sel_hi:[1,1,0]
	v_lshlrev_b32_e32 v2, 16, v9
	v_and_b32_e32 v3, 0xffff0000, v9
	v_pk_fma_f32 v[2:3], v[12:13], v[2:3], 0 op_sel_hi:[1,1,0]
	v_pk_fma_f32 v[14:15], v[14:15], v[20:21], 0 op_sel_hi:[1,1,0]
	v_mov_b32_e32 v26, v2
	v_mov_b32_e32 v27, v3
	s_or_b64 exec, exec, s[90:91]
	s_and_saveexec_b64 s[90:91], s[88:89]
	s_cbranch_execz .LBB0_334
; #define LAS __attribute__((address_space(3)))
; __device__ __forceinline__ float bflo(unsigned w) { return __uint_as_float(w << 16); }
; __device__ __forceinline__ float bfhi(unsigned w) { return __uint_as_float(w & 0xffff0000u); }
; __device__ __forceinline__ void gdn_prep_wg(const bf16* P, const float* SMALL, const float* conv_w, const float* a_log, const float* dt_bias,
;                                             unsigned char* REC, bf16* UF, float* EG, LAS unsigned char* lds, int bh, int n0, int nch) {
;     ...
;                 for (int i = 0; i < 4; ++i) {
;                     if (t - 3 + i >= 0) { const LAS unsigned char* src = raw + (row + i) * RAWP + ten * 256 + c0 * 2; const v4u x0 = *(const LAS v4u*)src, x1 = *(const LAS v4u*)(src + 16);
;                         const float* w = conv_w + (size_t)i * CONVW + pcol;
;                         const f32x4 w0 = *(const f32x4*)w, w1 = *(const f32x4*)(w + 4), w2 = *(const f32x4*)(w + 8), w3 = *(const f32x4*)(w + 12);
;                         acc[0] += w0.x * bflo(x0.x); acc[1] += w0.y * bfhi(x0.x); acc[2] += w0.z * bflo(x0.y); acc[3] += w0.w * bfhi(x0.y);
;                         acc[4] += w1.x * bflo(x0.z); acc[5] += w1.y * bfhi(x0.z); acc[6] += w1.z * bflo(x0.w); acc[7] += w1.w * bfhi(x0.w);
;                         acc[8] += w2.x * bflo(x1.x); acc[9] += w2.y * bfhi(x1.x); acc[10] += w2.z * bflo(x1.y); acc[11] += w2.w * bfhi(x1.y);
;                         acc[12] += w3.x * bflo(x1.z); acc[13] += w3.y * bfhi(x1.z); acc[14] += w3.z * bflo(x1.w); acc[15] += w3.w * bfhi(x1.w); } }
.LBB0_380:
	ds_read_b128 v[4:7], v201 offset:1040
	ds_read_b128 v[8:11], v201 offset:1056
	ds_read_b128 v[36:39], v230 offset:2608
	ds_read_b128 v[44:47], v230 offset:2592
	ds_read_b128 v[48:51], v230 offset:2576
	ds_read_b128 v[52:55], v230 offset:2560
	s_waitcnt lgkmcnt(1)
	v_lshlrev_b32_e32 v12, 16, v4
	v_and_b32_e32 v13, 0xffff0000, v4
	v_lshlrev_b32_e32 v4, 16, v5
	v_and_b32_e32 v5, 0xffff0000, v5
	s_waitcnt vmcnt(0) lgkmcnt(0)
	v_pk_fma_f32 v[16:17], v[54:55], v[4:5], v[16:17]
	v_lshlrev_b32_e32 v4, 16, v6
	v_and_b32_e32 v5, 0xffff0000, v6
	v_pk_fma_f32 v[22:23], v[48:49], v[4:5], v[22:23]
	v_lshlrev_b32_e32 v4, 16, v7
	v_and_b32_e32 v5, 0xffff0000, v7
	v_pk_fma_f32 v[24:25], v[50:51], v[4:5], v[24:25]
	s_waitcnt lgkmcnt(0)
	v_lshlrev_b32_e32 v4, 16, v8
	v_and_b32_e32 v5, 0xffff0000, v8
	v_pk_fma_f32 v[28:29], v[44:45], v[4:5], v[28:29]
	v_lshlrev_b32_e32 v4, 16, v9
	v_and_b32_e32 v5, 0xffff0000, v9
	v_pk_fma_f32 v[34:35], v[46:47], v[4:5], v[34:35]
	v_lshlrev_b32_e32 v4, 16, v10
	v_and_b32_e32 v5, 0xffff0000, v10
	v_pk_fma_f32 v[30:31], v[36:37], v[4:5], v[30:31]
	v_lshlrev_b32_e32 v4, 16, v11
	v_and_b32_e32 v5, 0xffff0000, v11
	v_pk_fma_f32 v[14:15], v[52:53], v[12:13], v[14:15]
	v_pk_fma_f32 v[26:27], v[38:39], v[4:5], v[2:3]
	s_or_b64 exec, exec, s[90:91]
	s_and_saveexec_b64 s[90:91], s[84:85]
	s_cbranch_execnz .LBB0_335
	s_branch .LBB0_336
.LBB0_381:
	ds_read_b128 v[2:5], v201 offset:512
	ds_read_b128 v[6:9], v201 offset:528
	ds_read_b128 v[10:13], v230 offset:4144
	ds_read_b128 v[14:17], v230 offset:4128
	ds_read_b128 v[24:27], v230 offset:4112
	ds_read_b128 v[20:23], v230 offset:4096
	s_waitcnt lgkmcnt(1)
	v_lshlrev_b32_e32 v28, 16, v2
	v_and_b32_e32 v29, 0xffff0000, v2
	v_lshlrev_b32_e32 v2, 16, v3
	v_and_b32_e32 v3, 0xffff0000, v3
	s_waitcnt vmcnt(0) lgkmcnt(0)
	v_pk_fma_f32 v[22:23], v[22:23], v[2:3], 0 op_sel_hi:[1,1,0]
	v_lshlrev_b32_e32 v2, 16, v4
	v_and_b32_e32 v3, 0xffff0000, v4
	v_pk_fma_f32 v[24:25], v[24:25], v[2:3], 0 op_sel_hi:[1,1,0]
	v_lshlrev_b32_e32 v2, 16, v5
	v_and_b32_e32 v3, 0xffff0000, v5
	v_pk_fma_f32 v[26:27], v[26:27], v[2:3], 0 op_sel_hi:[1,1,0]
	s_waitcnt lgkmcnt(0)
	v_lshlrev_b32_e32 v2, 16, v6
	v_and_b32_e32 v3, 0xffff0000, v6
	v_pk_fma_f32 v[20:21], v[20:21], v[28:29], 0 op_sel_hi:[1,1,0]
	v_pk_fma_f32 v[28:29], v[14:15], v[2:3], 0 op_sel_hi:[1,1,0]
	v_lshlrev_b32_e32 v2, 16, v7
	v_and_b32_e32 v3, 0xffff0000, v7
	v_pk_fma_f32 v[30:31], v[16:17], v[2:3], 0 op_sel_hi:[1,1,0]
	v_lshlrev_b32_e32 v2, 16, v8
	v_and_b32_e32 v3, 0xffff0000, v8
	v_pk_fma_f32 v[32:33], v[10:11], v[2:3], 0 op_sel_hi:[1,1,0]
	v_lshlrev_b32_e32 v2, 16, v9
	v_and_b32_e32 v3, 0xffff0000, v9
	v_pk_fma_f32 v[2:3], v[12:13], v[2:3], 0 op_sel_hi:[1,1,0]
	s_nop 0
	v_mov_b32_e32 v34, v2
	v_mov_b32_e32 v35, v3
	s_or_b64 exec, exec, s[90:91]
	s_and_saveexec_b64 s[86:87], s[88:89]
	s_cbranch_execz .LBB0_338
.LBB0_382:
	ds_read_b128 v[4:7], v201 offset:1296
	ds_read_b128 v[8:11], v201 offset:1312
	ds_read_b128 v[12:15], v230 offset:4656
	ds_read_b128 v[34:37], v230 offset:4640
	ds_read_b128 v[38:41], v230 offset:4624
	ds_read_b128 v[42:45], v230 offset:4608
	s_waitcnt lgkmcnt(1)
	v_lshlrev_b32_e32 v16, 16, v4
	v_and_b32_e32 v17, 0xffff0000, v4
	v_lshlrev_b32_e32 v4, 16, v5
	v_and_b32_e32 v5, 0xffff0000, v5
	s_waitcnt vmcnt(0) lgkmcnt(0)
	v_pk_fma_f32 v[22:23], v[44:45], v[4:5], v[22:23]
	v_lshlrev_b32_e32 v4, 16, v6
	v_and_b32_e32 v5, 0xffff0000, v6
	v_pk_fma_f32 v[24:25], v[38:39], v[4:5], v[24:25]
	v_lshlrev_b32_e32 v4, 16, v7
	v_and_b32_e32 v5, 0xffff0000, v7
	v_pk_fma_f32 v[26:27], v[40:41], v[4:5], v[26:27]
	s_waitcnt lgkmcnt(0)
	v_lshlrev_b32_e32 v4, 16, v8
	v_and_b32_e32 v5, 0xffff0000, v8
	v_pk_fma_f32 v[28:29], v[34:35], v[4:5], v[28:29]
	v_lshlrev_b32_e32 v4, 16, v9
	v_and_b32_e32 v5, 0xffff0000, v9
	v_pk_fma_f32 v[30:31], v[36:37], v[4:5], v[30:31]
	v_lshlrev_b32_e32 v4, 16, v10
	v_and_b32_e32 v5, 0xffff0000, v10
	v_pk_fma_f32 v[32:33], v[12:13], v[4:5], v[32:33]
	v_lshlrev_b32_e32 v4, 16, v11
	v_and_b32_e32 v5, 0xffff0000, v11
	v_pk_fma_f32 v[20:21], v[42:43], v[16:17], v[20:21]
	v_pk_fma_f32 v[34:35], v[14:15], v[4:5], v[2:3]
	s_or_b64 exec, exec, s[86:87]
	s_and_saveexec_b64 s[86:87], s[84:85]
	s_cbranch_execnz .LBB0_339
	s_branch .LBB0_340
